# v33 + redundant lgkmcnt(0) after the start-of-MMA barrier removed
# speedup vs baseline: 1.0114x; 1.0114x over previous
; template <class Epi, class Sched, bool ALIGN_EPI = false, bool SP2 = false>
; __device__ __forceinline__ void gemm_phase(PG8_LAS unsigned char* lds, const Gemm g, const Sched& S, const Epi& E) {
;     ...
;         const bool has_next = S.next(ui + 1, nxt);
;         const char* nA = has_next ? (const char*)g.A + (size_t)nxt.pm * tstepA : cA; const char* nB = has_next ? (const char*)g.Bt + (size_t)nxt.pn * tstepB : cB;
;     ...
;         if constexpr (Epi::PEEL) {
;             const char* a1 = cA + kstepA; const char* a2 = cA + 2 * kstepA; const char* b2 = cB + 2 * kstepB; const char* a3 = a2 + kstepA; const char* b3 = b2 + kstepB;
;             PG8_ITER(8);
.LBB0_160:
	s_ashr_i32 s55, s54, 31
	s_lshl_b64 s[2:3], s[54:55], 15
	v_readlane_b32 s8, v255, 15
	s_add_u32 s12, s8, s2
	v_readlane_b32 s2, v255, 16
	s_addc_u32 s13, s2, s3
	s_ashr_i32 s49, s48, 31
	s_lshl_b64 s[2:3], s[48:49], 19
	v_readlane_b32 s8, v255, 29
	s_add_u32 s46, s8, s2
	v_readlane_b32 s2, v255, 40
	s_addc_u32 s47, s2, s3
	s_add_u32 s28, s24, 0x800000
	s_addc_u32 s29, s25, 0
	s_add_u32 s42, s24, 0xc00000
	s_addc_u32 s43, s25, 0
	s_add_i32 s55, 0, 0x10000
	s_and_b64 s[2:3], s[30:31], exec
	s_cselect_b32 s27, s13, s25
	s_cselect_b32 s44, s12, s24
	s_add_i32 vcc_hi, 0, 0x14000
	v_add_u32_e32 v142, s55, v97
	v_add_u32_e32 v143, vcc_hi, v97
	ds_read_b128 v[0:3], v142
	ds_read_b128 v[4:7], v142 offset:1024
	ds_read_b128 v[8:11], v142 offset:2048
	ds_read_b128 v[12:15], v142 offset:3072
	ds_read_b128 v[16:19], v143
	s_waitcnt lgkmcnt(0)
	ds_read_b128 v[20:23], v143 offset:1024
	ds_read_b128 v[24:27], v143 offset:2048
	ds_read_b128 v[28:31], v143 offset:3072
	v_writelane_b32 v255, s30, 33
	s_and_b64 s[2:3], s[30:31], exec
	s_cselect_b32 s45, s47, s1
	v_writelane_b32 v255, s31, 34
	s_cselect_b32 s49, s46, s0
	s_add_u32 s2, s24, 0x404000
	s_addc_u32 s3, s25, 0
	s_add_i32 s50, s22, 0xc000
	s_mov_b32 m0, s50
	s_add_i32 s51, s22, 0xe000
	ds_read_b128 v[32:35], v161
	ds_read_b128 v[36:39], v161 offset:1024
	ds_read_b128 v[40:43], v161 offset:2048
	ds_read_b128 v[44:47], v161 offset:3072
	ds_read_b128 v[48:51], v161 offset:4096
	ds_read_b128 v[52:55], v161 offset:5120
	ds_read_b128 v[56:59], v161 offset:6144
	ds_read_b128 v[60:63], v161 offset:7168
	global_load_lds_dwordx4 v130, s[2:3]
	s_mov_b32 m0, s51
	s_nop 0
	global_load_lds_dwordx4 v134, s[2:3]
	s_waitcnt vmcnt(8)
	s_waitcnt lgkmcnt(0)
	s_barrier
	v_mfma_f32_16x16x32_bf16 v[64:67], v[0:3], v[32:35], 0
	v_mfma_f32_16x16x32_bf16 v[68:71], v[8:11], v[32:35], 0
	v_mfma_f32_16x16x32_bf16 v[72:75], v[0:3], v[40:43], 0
	v_mfma_f32_16x16x32_bf16 v[76:79], v[8:11], v[40:43], 0
	v_mfma_f32_16x16x32_bf16 v[80:83], v[0:3], v[48:51], 0
	v_mfma_f32_16x16x32_bf16 v[84:87], v[8:11], v[48:51], 0
	v_mfma_f32_16x16x32_bf16 v[88:91], v[0:3], v[56:59], 0
	v_mfma_f32_16x16x32_bf16 v[92:95], v[8:11], v[56:59], 0
	v_mfma_f32_16x16x32_bf16 v[64:67], v[4:7], v[36:39], v[64:67]
	v_mfma_f32_16x16x32_bf16 v[68:71], v[12:15], v[36:39], v[68:71]
	v_mfma_f32_16x16x32_bf16 v[72:75], v[4:7], v[44:47], v[72:75]
	v_mfma_f32_16x16x32_bf16 v[76:79], v[12:15], v[44:47], v[76:79]
	v_mfma_f32_16x16x32_bf16 v[80:83], v[4:7], v[52:55], v[80:83]
	v_mfma_f32_16x16x32_bf16 v[84:87], v[12:15], v[52:55], v[84:87]
	v_mfma_f32_16x16x32_bf16 v[88:91], v[4:7], v[60:63], v[88:91]
	v_mfma_f32_16x16x32_bf16 v[98:101], v[12:15], v[60:63], v[92:95]
	v_mfma_f32_16x16x32_bf16 v[92:95], v[16:19], v[32:35], 0
	v_mfma_f32_16x16x32_bf16 v[32:35], v[24:27], v[32:35], 0
	v_mfma_f32_16x16x32_bf16 v[106:109], v[20:23], v[36:39], v[92:95]
	v_mfma_f32_16x16x32_bf16 v[32:35], v[28:31], v[36:39], v[32:35]
	v_mfma_f32_16x16x32_bf16 v[36:39], v[16:19], v[40:43], 0
	v_mfma_f32_16x16x32_bf16 v[40:43], v[24:27], v[40:43], 0
	v_mfma_f32_16x16x32_bf16 v[36:39], v[20:23], v[44:47], v[36:39]
	v_mfma_f32_16x16x32_bf16 v[40:43], v[28:31], v[44:47], v[40:43]
	v_mfma_f32_16x16x32_bf16 v[44:47], v[16:19], v[48:51], 0
	v_mfma_f32_16x16x32_bf16 v[48:51], v[24:27], v[48:51], 0
	v_mfma_f32_16x16x32_bf16 v[44:47], v[20:23], v[52:55], v[44:47]
	v_mfma_f32_16x16x32_bf16 v[48:51], v[28:31], v[52:55], v[48:51]
	v_mfma_f32_16x16x32_bf16 v[52:55], v[16:19], v[56:59], 0
	v_mfma_f32_16x16x32_bf16 v[56:59], v[24:27], v[56:59], 0
	v_mfma_f32_16x16x32_bf16 v[52:55], v[20:23], v[60:63], v[52:55]
	v_mfma_f32_16x16x32_bf16 v[56:59], v[28:31], v[60:63], v[56:59]
	s_barrier
	v_lshl_add_u64 v[158:159], s[0:1], 0, v[132:133]
	s_mov_b64 s[2:3], 0x100
	s_add_i32 s55, s55, s10
	v_lshl_add_u64 v[144:145], v[158:159], 0, s[2:3]
	s_mov_b32 m0, s55
	v_lshl_add_u64 v[178:179], s[0:1], 0, v[136:137]
	s_add_i32 vcc_lo, s55, 0x2000
	ds_read_b128 v[60:63], v161 offset:16384
	ds_read_b128 v[92:95], v161 offset:17408
	ds_read_b128 v[102:105], v161 offset:18432
	ds_read_b128 v[110:113], v161 offset:19456
	ds_read_b128 v[114:117], v161 offset:20480
	ds_read_b128 v[118:121], v161 offset:21504
	ds_read_b128 v[122:125], v161 offset:22528
	ds_read_b128 v[126:129], v161 offset:23552
	global_load_lds_dwordx4 v[144:145], off
	v_lshl_add_u64 v[144:145], v[178:179], 0, s[2:3]
	s_add_u32 s2, s0, 0x40100
	s_mov_b32 m0, vcc_lo
	s_addc_u32 s3, s1, 0
	s_add_i32 vcc_hi, vcc_hi, s10
	global_load_lds_dwordx4 v[144:145], off
	s_mov_b32 m0, vcc_hi
	s_add_i32 s56, vcc_hi, 0x2000
	global_load_lds_dwordx4 v132, s[2:3]
	s_mov_b32 m0, s56
	s_nop 0
	global_load_lds_dwordx4 v136, s[2:3]
	s_mov_b32 m0, s22
	s_nop 0
	global_load_lds_dwordx4 v130, s[28:29]
	s_mov_b32 m0, s23
	s_nop 0
	global_load_lds_dwordx4 v134, s[28:29]
	s_waitcnt vmcnt(8)
	s_waitcnt lgkmcnt(0)
	s_barrier
	v_mfma_f32_16x16x32_bf16 v[144:147], v[0:3], v[60:63], 0
	v_mfma_f32_16x16x32_bf16 v[154:157], v[0:3], v[102:105], 0
	v_mfma_f32_16x16x32_bf16 v[166:169], v[0:3], v[114:117], 0
	v_mfma_f32_16x16x32_bf16 v[0:3], v[0:3], v[122:125], 0
	v_mfma_f32_16x16x32_bf16 v[146:149], v[4:7], v[92:95], v[144:147]
	v_mfma_f32_16x16x32_bf16 v[154:157], v[4:7], v[110:113], v[154:157]
	v_mfma_f32_16x16x32_bf16 v[166:169], v[4:7], v[118:121], v[166:169]
	v_mfma_f32_16x16x32_bf16 v[0:3], v[4:7], v[126:129], v[0:3]
	v_mfma_f32_16x16x32_bf16 v[4:7], v[8:11], v[122:125], 0
	v_mfma_f32_16x16x32_bf16 v[150:153], v[8:11], v[60:63], 0
	v_mfma_f32_16x16x32_bf16 v[162:165], v[8:11], v[102:105], 0
	v_mfma_f32_16x16x32_bf16 v[170:173], v[8:11], v[114:117], 0
	v_mfma_f32_16x16x32_bf16 v[4:7], v[12:15], v[126:129], v[4:7]
	v_mfma_f32_16x16x32_bf16 v[150:153], v[12:15], v[92:95], v[150:153]
	v_mfma_f32_16x16x32_bf16 v[162:165], v[12:15], v[110:113], v[162:165]
	v_mfma_f32_16x16x32_bf16 v[170:173], v[12:15], v[118:121], v[170:173]
	v_mfma_f32_16x16x32_bf16 v[12:15], v[24:27], v[60:63], 0
	v_mfma_f32_16x16x32_bf16 v[174:177], v[28:31], v[92:95], v[12:15]
	v_mfma_f32_16x16x32_bf16 v[12:15], v[16:19], v[102:105], 0
	v_mfma_f32_16x16x32_bf16 v[180:183], v[20:23], v[110:113], v[12:15]
	v_mfma_f32_16x16x32_bf16 v[12:15], v[24:27], v[102:105], 0
	v_mfma_f32_16x16x32_bf16 v[184:187], v[28:31], v[110:113], v[12:15]
	v_mfma_f32_16x16x32_bf16 v[12:15], v[16:19], v[114:117], 0
	v_mfma_f32_16x16x32_bf16 v[188:191], v[20:23], v[118:121], v[12:15]
	v_mfma_f32_16x16x32_bf16 v[12:15], v[24:27], v[114:117], 0
	v_mfma_f32_16x16x32_bf16 v[8:11], v[16:19], v[60:63], 0
	v_mfma_f32_16x16x32_bf16 v[192:195], v[28:31], v[118:121], v[12:15]
	v_mfma_f32_16x16x32_bf16 v[12:15], v[16:19], v[122:125], 0
	v_mfma_f32_16x16x32_bf16 v[8:11], v[20:23], v[92:95], v[8:11]
	v_mfma_f32_16x16x32_bf16 v[196:199], v[20:23], v[126:129], v[12:15]
	v_mfma_f32_16x16x32_bf16 v[12:15], v[24:27], v[122:125], 0
	v_mfma_f32_16x16x32_bf16 v[200:203], v[28:31], v[126:129], v[12:15]
	s_barrier
	s_add_i32 s30, 0, 0x18000
	s_add_i32 s57, 0, 0x1c000
	v_add_u32_e32 v144, s30, v97
	v_add_u32_e32 v145, s57, v97
	s_nop 0
	ds_read_b128 v[12:15], v144
	ds_read_b128 v[16:19], v144 offset:1024
	ds_read_b128 v[24:27], v144 offset:2048
	ds_read_b128 v[204:207], v144 offset:3072
	ds_read_b128 v[208:211], v145
	ds_read_b128 v[212:215], v145 offset:1024
	ds_read_b128 v[216:219], v145 offset:2048
	ds_read_b128 v[220:223], v145 offset:3072
	s_add_u32 s2, s24, 0x804000
	s_addc_u32 s3, s25, 0
	s_mov_b32 m0, s39
	ds_read_b128 v[20:23], v161 offset:32768
	ds_read_b128 v[28:31], v161 offset:33792
	ds_read_b128 v[60:63], v161 offset:34816
	ds_read_b128 v[224:227], v161 offset:35840
	ds_read_b128 v[228:231], v161 offset:36864
	ds_read_b128 v[234:237], v161 offset:37888
	ds_read_b128 v[238:241], v161 offset:38912
	ds_read_b128 v[242:245], v161 offset:39936
	global_load_lds_dwordx4 v130, s[2:3]
	s_mov_b32 m0, s52
	s_nop 0
	global_load_lds_dwordx4 v134, s[2:3]
	s_waitcnt vmcnt(8)
	s_waitcnt lgkmcnt(0)
	s_barrier
	v_mfma_f32_16x16x32_bf16 v[64:67], v[12:15], v[20:23], v[64:67]
	v_mfma_f32_16x16x32_bf16 v[126:129], v[16:19], v[28:31], v[64:67]
	v_mfma_f32_16x16x32_bf16 v[64:67], v[24:27], v[20:23], v[68:71]
	v_mfma_f32_16x16x32_bf16 v[118:121], v[204:207], v[28:31], v[64:67]
	v_mfma_f32_16x16x32_bf16 v[64:67], v[12:15], v[60:63], v[72:75]
	v_mfma_f32_16x16x32_bf16 v[110:113], v[16:19], v[224:227], v[64:67]
	v_mfma_f32_16x16x32_bf16 v[64:67], v[24:27], v[60:63], v[76:79]
	v_mfma_f32_16x16x32_bf16 v[102:105], v[204:207], v[224:227], v[64:67]
	v_mfma_f32_16x16x32_bf16 v[64:67], v[12:15], v[228:231], v[80:83]
	v_mfma_f32_16x16x32_bf16 v[92:95], v[16:19], v[234:237], v[64:67]
	v_mfma_f32_16x16x32_bf16 v[64:67], v[24:27], v[228:231], v[84:87]
	v_mfma_f32_16x16x32_bf16 v[84:87], v[204:207], v[234:237], v[64:67]
	v_mfma_f32_16x16x32_bf16 v[64:67], v[12:15], v[238:241], v[88:91]
	v_mfma_f32_16x16x32_bf16 v[76:79], v[16:19], v[242:245], v[64:67]
	v_mfma_f32_16x16x32_bf16 v[64:67], v[24:27], v[238:241], v[98:101]
	v_mfma_f32_16x16x32_bf16 v[68:71], v[204:207], v[242:245], v[64:67]
	v_mfma_f32_16x16x32_bf16 v[64:67], v[208:211], v[20:23], v[106:109]
	v_mfma_f32_16x16x32_bf16 v[20:23], v[216:219], v[20:23], v[32:35]
	v_mfma_f32_16x16x32_bf16 v[114:117], v[220:223], v[28:31], v[20:23]
	v_mfma_f32_16x16x32_bf16 v[20:23], v[208:211], v[60:63], v[36:39]
	v_mfma_f32_16x16x32_bf16 v[106:109], v[212:215], v[224:227], v[20:23]
	v_mfma_f32_16x16x32_bf16 v[20:23], v[216:219], v[60:63], v[40:43]
	v_mfma_f32_16x16x32_bf16 v[98:101], v[220:223], v[224:227], v[20:23]
	v_mfma_f32_16x16x32_bf16 v[20:23], v[208:211], v[228:231], v[44:47]
	v_mfma_f32_16x16x32_bf16 v[88:91], v[212:215], v[234:237], v[20:23]
	v_mfma_f32_16x16x32_bf16 v[20:23], v[216:219], v[228:231], v[48:51]
	v_mfma_f32_16x16x32_bf16 v[80:83], v[220:223], v[234:237], v[20:23]
	v_mfma_f32_16x16x32_bf16 v[20:23], v[208:211], v[238:241], v[52:55]
	v_mfma_f32_16x16x32_bf16 v[72:75], v[212:215], v[242:245], v[20:23]
	v_mfma_f32_16x16x32_bf16 v[20:23], v[216:219], v[238:241], v[56:59]
	v_mfma_f32_16x16x32_bf16 v[122:125], v[212:215], v[28:31], v[64:67]
	v_mfma_f32_16x16x32_bf16 v[64:67], v[220:223], v[242:245], v[20:23]
	s_barrier
; template <class Epi, class Sched, bool ALIGN_EPI = false, bool SP2 = false>
; __device__ __forceinline__ void gemm_phase(PG8_LAS unsigned char* lds, const Gemm g, const Sched& S, const Epi& E) {
;     ...
;         if constexpr (Epi::PEEL) {
;             const char* a1 = cA + kstepA; const char* a2 = cA + 2 * kstepA; const char* b2 = cB + 2 * kstepB; const char* a3 = a2 + kstepA; const char* b3 = b2 + kstepB;
;             PG8_ITER(8);
;         }
;         for (int t = (Epi::PEEL ? 2 : 0); t < nt; t += 2) {
;             const bool last = (t == nt - 2);
;             const char* a1 = cA + (size_t)(t + 1) * kstepA;
;             const char* a2 = last ? nA : cA + (size_t)(t + 2) * kstepA; const char* b2 = last ? nB : cB + (size_t)(t + 2) * kstepB;
;             const char* a3 = a2 + kstepA; const char* b3 = b2 + kstepB;
;             PG8_ITER(8);
	s_mov_b64 s[2:3], 0x180
	s_add_i32 s30, s30, s10
	s_nop 1
	v_lshl_add_u64 v[20:21], v[158:159], 0, s[2:3]
	s_mov_b32 m0, s30
	s_add_i32 s31, s30, 0x2000
	ds_read_b128 v[32:35], v161 offset:49152
	ds_read_b128 v[40:43], v161 offset:50176
	ds_read_b128 v[224:227], v161 offset:51200
	ds_read_b128 v[228:231], v161 offset:52224
	ds_read_b128 v[234:237], v161 offset:53248
	ds_read_b128 v[238:241], v161 offset:54272
	ds_read_b128 v[242:245], v161 offset:55296
	ds_read_b128 v[246:249], v161 offset:56320
	global_load_lds_dwordx4 v[20:21], off
	v_lshl_add_u64 v[20:21], v[178:179], 0, s[2:3]
	s_add_u32 s2, s0, 0x40180
	s_mov_b32 m0, s31
	s_addc_u32 s3, s1, 0
	s_add_i32 s57, s57, s10
	global_load_lds_dwordx4 v[20:21], off
	s_mov_b32 m0, s57
	s_add_i32 s96, s57, 0x2000
	global_load_lds_dwordx4 v132, s[2:3]
	s_mov_b32 m0, s96
	s_nop 0
	global_load_lds_dwordx4 v136, s[2:3]
	s_mov_b32 m0, s11
	s_nop 0
	global_load_lds_dwordx4 v130, s[42:43]
	s_mov_b32 m0, s19
	s_nop 0
	global_load_lds_dwordx4 v134, s[42:43]
	s_waitcnt vmcnt(8)
	s_waitcnt lgkmcnt(0)
	s_barrier
	v_mfma_f32_16x16x32_bf16 v[20:23], v[12:15], v[32:35], v[146:149]
	v_mfma_f32_16x16x32_bf16 v[60:63], v[16:19], v[40:43], v[20:23]
	v_mfma_f32_16x16x32_bf16 v[20:23], v[24:27], v[32:35], v[150:153]
	v_mfma_f32_16x16x32_bf16 v[52:55], v[204:207], v[40:43], v[20:23]
	v_mfma_f32_16x16x32_bf16 v[20:23], v[12:15], v[224:227], v[154:157]
	v_mfma_f32_16x16x32_bf16 v[44:47], v[16:19], v[228:231], v[20:23]
	v_mfma_f32_16x16x32_bf16 v[20:23], v[24:27], v[224:227], v[162:165]
	v_mfma_f32_16x16x32_bf16 v[36:39], v[204:207], v[228:231], v[20:23]
	v_mfma_f32_16x16x32_bf16 v[20:23], v[12:15], v[234:237], v[166:169]
	v_mfma_f32_16x16x32_bf16 v[0:3], v[12:15], v[242:245], v[0:3]
	v_mfma_f32_16x16x32_bf16 v[28:31], v[16:19], v[238:241], v[20:23]
	v_mfma_f32_16x16x32_bf16 v[20:23], v[24:27], v[234:237], v[170:173]
	v_mfma_f32_16x16x32_bf16 v[12:15], v[16:19], v[246:249], v[0:3]
	v_mfma_f32_16x16x32_bf16 v[0:3], v[24:27], v[242:245], v[4:7]
	v_mfma_f32_16x16x32_bf16 v[20:23], v[204:207], v[238:241], v[20:23]
	v_mfma_f32_16x16x32_bf16 v[4:7], v[204:207], v[246:249], v[0:3]
	v_mfma_f32_16x16x32_bf16 v[0:3], v[208:211], v[32:35], v[8:11]
	v_mfma_f32_16x16x32_bf16 v[56:59], v[212:215], v[40:43], v[0:3]
	v_mfma_f32_16x16x32_bf16 v[0:3], v[216:219], v[32:35], v[174:177]
	v_mfma_f32_16x16x32_bf16 v[48:51], v[220:223], v[40:43], v[0:3]
	v_mfma_f32_16x16x32_bf16 v[0:3], v[208:211], v[224:227], v[180:183]
	v_mfma_f32_16x16x32_bf16 v[40:43], v[212:215], v[228:231], v[0:3]
	v_mfma_f32_16x16x32_bf16 v[0:3], v[216:219], v[224:227], v[184:187]
	v_mfma_f32_16x16x32_bf16 v[32:35], v[220:223], v[228:231], v[0:3]
	v_mfma_f32_16x16x32_bf16 v[0:3], v[208:211], v[234:237], v[188:191]
	v_mfma_f32_16x16x32_bf16 v[24:27], v[212:215], v[238:241], v[0:3]
	v_mfma_f32_16x16x32_bf16 v[0:3], v[216:219], v[234:237], v[192:195]
	v_mfma_f32_16x16x32_bf16 v[16:19], v[220:223], v[238:241], v[0:3]
	v_mfma_f32_16x16x32_bf16 v[0:3], v[208:211], v[242:245], v[196:199]
	v_mfma_f32_16x16x32_bf16 v[8:11], v[212:215], v[246:249], v[0:3]
	v_mfma_f32_16x16x32_bf16 v[0:3], v[216:219], v[242:245], v[200:203]
	v_mfma_f32_16x16x32_bf16 v[0:3], v[220:223], v[246:249], v[0:3]
	s_barrier
	s_add_u32 s3, s0, 0x200
	s_addc_u32 s2, s1, 0
	s_add_u32 s0, s24, 0xc04000
	s_addc_u32 s1, s25, 0
	s_mov_b32 s18, 0
.LBB0_161:
	ds_read_b128 v[146:149], v142
	ds_read_b128 v[150:153], v142 offset:1024
	ds_read_b128 v[154:157], v142 offset:2048
	ds_read_b128 v[162:165], v142 offset:3072
	ds_read_b128 v[166:169], v143
	ds_read_b128 v[170:173], v143 offset:1024
	ds_read_b128 v[174:177], v143 offset:2048
	ds_read_b128 v[180:183], v143 offset:3072
	s_add_u32 s8, s0, 0x3fc000
	s_addc_u32 s9, s1, 0
	s_cmp_eq_u32 s18, 12
	s_cselect_b32 s28, s44, s8
	s_cselect_b32 s29, s27, s9
	s_cselect_b32 s42, s49, s3
	s_cselect_b32 s43, s45, s2
	s_add_u32 s24, s28, 0x400000
	s_addc_u32 s25, s29, 0
	s_mov_b32 m0, s50
	ds_read_b128 v[184:187], v161
	ds_read_b128 v[188:191], v161 offset:1024
	ds_read_b128 v[192:195], v161 offset:2048
	ds_read_b128 v[196:199], v161 offset:3072
	ds_read_b128 v[200:203], v161 offset:4096
	ds_read_b128 v[204:207], v161 offset:5120
	ds_read_b128 v[208:211], v161 offset:6144
	ds_read_b128 v[212:215], v161 offset:7168
	global_load_lds_dwordx4 v140, s[0:1]
	s_mov_b32 m0, s51
	s_nop 0
	global_load_lds_dwordx4 v138, s[0:1]
	s_waitcnt vmcnt(8)
	s_waitcnt lgkmcnt(0)
	s_barrier
	v_mfma_f32_16x16x32_bf16 v[126:129], v[146:149], v[184:187], v[126:129]
	v_mfma_f32_16x16x32_bf16 v[118:121], v[154:157], v[184:187], v[118:121]
	v_mfma_f32_16x16x32_bf16 v[102:105], v[154:157], v[192:195], v[102:105]
	v_mfma_f32_16x16x32_bf16 v[110:113], v[146:149], v[192:195], v[110:113]
	v_mfma_f32_16x16x32_bf16 v[92:95], v[146:149], v[200:203], v[92:95]
	v_mfma_f32_16x16x32_bf16 v[84:87], v[154:157], v[200:203], v[84:87]
	v_mfma_f32_16x16x32_bf16 v[68:71], v[154:157], v[208:211], v[68:71]
	v_mfma_f32_16x16x32_bf16 v[76:79], v[146:149], v[208:211], v[76:79]
	v_mfma_f32_16x16x32_bf16 v[126:129], v[150:153], v[188:191], v[126:129]
	v_mfma_f32_16x16x32_bf16 v[118:121], v[162:165], v[188:191], v[118:121]
	v_mfma_f32_16x16x32_bf16 v[102:105], v[162:165], v[196:199], v[102:105]
	v_mfma_f32_16x16x32_bf16 v[110:113], v[150:153], v[196:199], v[110:113]
	v_mfma_f32_16x16x32_bf16 v[92:95], v[150:153], v[204:207], v[92:95]
	v_mfma_f32_16x16x32_bf16 v[84:87], v[162:165], v[204:207], v[84:87]
	v_mfma_f32_16x16x32_bf16 v[68:71], v[162:165], v[212:215], v[68:71]
	v_mfma_f32_16x16x32_bf16 v[76:79], v[150:153], v[212:215], v[76:79]
	v_mfma_f32_16x16x32_bf16 v[122:125], v[166:169], v[184:187], v[122:125]
	v_mfma_f32_16x16x32_bf16 v[114:117], v[174:177], v[184:187], v[114:117]
	v_mfma_f32_16x16x32_bf16 v[98:101], v[174:177], v[192:195], v[98:101]
	v_mfma_f32_16x16x32_bf16 v[106:109], v[166:169], v[192:195], v[106:109]
	v_mfma_f32_16x16x32_bf16 v[88:91], v[166:169], v[200:203], v[88:91]
	v_mfma_f32_16x16x32_bf16 v[80:83], v[174:177], v[200:203], v[80:83]
	v_mfma_f32_16x16x32_bf16 v[64:67], v[174:177], v[208:211], v[64:67]
	v_mfma_f32_16x16x32_bf16 v[72:75], v[166:169], v[208:211], v[72:75]
	v_mfma_f32_16x16x32_bf16 v[122:125], v[170:173], v[188:191], v[122:125]
	v_mfma_f32_16x16x32_bf16 v[114:117], v[180:183], v[188:191], v[114:117]
	v_mfma_f32_16x16x32_bf16 v[98:101], v[180:183], v[196:199], v[98:101]
	v_mfma_f32_16x16x32_bf16 v[106:109], v[170:173], v[196:199], v[106:109]
	v_mfma_f32_16x16x32_bf16 v[88:91], v[170:173], v[204:207], v[88:91]
	v_mfma_f32_16x16x32_bf16 v[80:83], v[180:183], v[204:207], v[80:83]
	v_mfma_f32_16x16x32_bf16 v[64:67], v[180:183], v[212:215], v[64:67]
	v_mfma_f32_16x16x32_bf16 v[72:75], v[170:173], v[212:215], v[72:75]
	s_barrier
	s_mov_b32 m0, s55
	s_add_u32 s8, s42, 0x40000
	ds_read_b128 v[184:187], v161 offset:16384
	ds_read_b128 v[188:191], v161 offset:17408
	ds_read_b128 v[192:195], v161 offset:18432
	ds_read_b128 v[196:199], v161 offset:19456
	ds_read_b128 v[200:203], v161 offset:20480
	ds_read_b128 v[204:207], v161 offset:21504
	ds_read_b128 v[208:211], v161 offset:22528
	ds_read_b128 v[212:215], v161 offset:23552
	global_load_lds_dwordx4 v132, s[42:43]
	s_mov_b32 m0, vcc_lo
	s_addc_u32 s9, s43, 0
	global_load_lds_dwordx4 v136, s[42:43]
	s_mov_b32 m0, vcc_hi
	s_nop 0
	global_load_lds_dwordx4 v132, s[8:9]
	s_mov_b32 m0, s56
	s_nop 0
	global_load_lds_dwordx4 v136, s[8:9]
	s_mov_b32 m0, s22
	s_nop 0
	global_load_lds_dwordx4 v130, s[28:29]
	s_mov_b32 m0, s23
	s_nop 0
	global_load_lds_dwordx4 v134, s[28:29]
	s_waitcnt vmcnt(8)
	s_waitcnt lgkmcnt(0)
	s_barrier
	v_mfma_f32_16x16x32_bf16 v[60:63], v[146:149], v[184:187], v[60:63]
	v_mfma_f32_16x16x32_bf16 v[52:55], v[154:157], v[184:187], v[52:55]
	v_mfma_f32_16x16x32_bf16 v[36:39], v[154:157], v[192:195], v[36:39]
	v_mfma_f32_16x16x32_bf16 v[44:47], v[146:149], v[192:195], v[44:47]
	v_mfma_f32_16x16x32_bf16 v[28:31], v[146:149], v[200:203], v[28:31]
	v_mfma_f32_16x16x32_bf16 v[20:23], v[154:157], v[200:203], v[20:23]
	v_mfma_f32_16x16x32_bf16 v[4:7], v[154:157], v[208:211], v[4:7]
	v_mfma_f32_16x16x32_bf16 v[12:15], v[146:149], v[208:211], v[12:15]
	v_mfma_f32_16x16x32_bf16 v[60:63], v[150:153], v[188:191], v[60:63]
	v_mfma_f32_16x16x32_bf16 v[52:55], v[162:165], v[188:191], v[52:55]
	v_mfma_f32_16x16x32_bf16 v[36:39], v[162:165], v[196:199], v[36:39]
	v_mfma_f32_16x16x32_bf16 v[44:47], v[150:153], v[196:199], v[44:47]
	v_mfma_f32_16x16x32_bf16 v[28:31], v[150:153], v[204:207], v[28:31]
	v_mfma_f32_16x16x32_bf16 v[20:23], v[162:165], v[204:207], v[20:23]
	v_mfma_f32_16x16x32_bf16 v[4:7], v[162:165], v[212:215], v[4:7]
	v_mfma_f32_16x16x32_bf16 v[12:15], v[150:153], v[212:215], v[12:15]
	v_mfma_f32_16x16x32_bf16 v[56:59], v[166:169], v[184:187], v[56:59]
	v_mfma_f32_16x16x32_bf16 v[48:51], v[174:177], v[184:187], v[48:51]
	v_mfma_f32_16x16x32_bf16 v[32:35], v[174:177], v[192:195], v[32:35]
	v_mfma_f32_16x16x32_bf16 v[40:43], v[166:169], v[192:195], v[40:43]
	v_mfma_f32_16x16x32_bf16 v[24:27], v[166:169], v[200:203], v[24:27]
	v_mfma_f32_16x16x32_bf16 v[16:19], v[174:177], v[200:203], v[16:19]
	v_mfma_f32_16x16x32_bf16 v[0:3], v[174:177], v[208:211], v[0:3]
	v_mfma_f32_16x16x32_bf16 v[8:11], v[166:169], v[208:211], v[8:11]
	v_mfma_f32_16x16x32_bf16 v[56:59], v[170:173], v[188:191], v[56:59]
	v_mfma_f32_16x16x32_bf16 v[48:51], v[180:183], v[188:191], v[48:51]
	v_mfma_f32_16x16x32_bf16 v[32:35], v[180:183], v[196:199], v[32:35]
	v_mfma_f32_16x16x32_bf16 v[40:43], v[170:173], v[196:199], v[40:43]
	v_mfma_f32_16x16x32_bf16 v[24:27], v[170:173], v[204:207], v[24:27]
	v_mfma_f32_16x16x32_bf16 v[16:19], v[180:183], v[204:207], v[16:19]
	v_mfma_f32_16x16x32_bf16 v[0:3], v[180:183], v[212:215], v[0:3]
	v_mfma_f32_16x16x32_bf16 v[8:11], v[170:173], v[212:215], v[8:11]
	s_barrier
	ds_read_b128 v[146:149], v144
	ds_read_b128 v[150:153], v144 offset:1024
	ds_read_b128 v[154:157], v144 offset:2048
	ds_read_b128 v[162:165], v144 offset:3072
	ds_read_b128 v[166:169], v145
	ds_read_b128 v[170:173], v145 offset:1024
	ds_read_b128 v[174:177], v145 offset:2048
	ds_read_b128 v[180:183], v145 offset:3072
	s_add_u32 s8, s28, 0x4000
	s_addc_u32 s9, s29, 0
	s_mov_b32 m0, s39
	ds_read_b128 v[184:187], v161 offset:32768
	ds_read_b128 v[188:191], v161 offset:33792
	ds_read_b128 v[192:195], v161 offset:34816
	ds_read_b128 v[196:199], v161 offset:35840
	ds_read_b128 v[200:203], v161 offset:36864
	ds_read_b128 v[204:207], v161 offset:37888
	ds_read_b128 v[208:211], v161 offset:38912
	ds_read_b128 v[212:215], v161 offset:39936
	global_load_lds_dwordx4 v130, s[8:9]
	s_mov_b32 m0, s52
	s_nop 0
	global_load_lds_dwordx4 v134, s[8:9]
	s_waitcnt vmcnt(8)
	s_waitcnt lgkmcnt(0)
	s_barrier
; #define PG8_BAR __builtin_amdgcn_s_barrier()
; template <class Epi, class Sched, bool ALIGN_EPI = false, bool SP2 = false>
; __device__ __forceinline__ void gemm_phase(PG8_LAS unsigned char* lds, const Gemm g, const Sched& S, const Epi& E) {
;     ...
;         if constexpr (Epi::PEEL) {
;             const char* a1 = cA + kstepA; const char* a2 = cA + 2 * kstepA; const char* b2 = cB + 2 * kstepB; const char* a3 = a2 + kstepA; const char* b3 = b2 + kstepB;
;             PG8_ITER(8);
;         }
;         for (int t = (Epi::PEEL ? 2 : 0); t < nt; t += 2) {
;             const bool last = (t == nt - 2);
;             const char* a1 = cA + (size_t)(t + 1) * kstepA;
;             const char* a2 = last ? nA : cA + (size_t)(t + 2) * kstepA; const char* b2 = last ? nB : cB + (size_t)(t + 2) * kstepB;
;             const char* a3 = a2 + kstepA; const char* b3 = b2 + kstepB;
;             PG8_ITER(8);
;         }
;     ...
;         if constexpr (ALIGN_EPI) { if (wr == 0) PG8_BAR; }
	v_mfma_f32_16x16x32_bf16 v[126:129], v[146:149], v[184:187], v[126:129]
	v_mfma_f32_16x16x32_bf16 v[118:121], v[154:157], v[184:187], v[118:121]
	v_mfma_f32_16x16x32_bf16 v[102:105], v[154:157], v[192:195], v[102:105]
	v_mfma_f32_16x16x32_bf16 v[110:113], v[146:149], v[192:195], v[110:113]
	v_mfma_f32_16x16x32_bf16 v[92:95], v[146:149], v[200:203], v[92:95]
	v_mfma_f32_16x16x32_bf16 v[84:87], v[154:157], v[200:203], v[84:87]
	v_mfma_f32_16x16x32_bf16 v[68:71], v[154:157], v[208:211], v[68:71]
	v_mfma_f32_16x16x32_bf16 v[76:79], v[146:149], v[208:211], v[76:79]
	v_mfma_f32_16x16x32_bf16 v[126:129], v[150:153], v[188:191], v[126:129]
	v_mfma_f32_16x16x32_bf16 v[118:121], v[162:165], v[188:191], v[118:121]
	v_mfma_f32_16x16x32_bf16 v[102:105], v[162:165], v[196:199], v[102:105]
	v_mfma_f32_16x16x32_bf16 v[110:113], v[150:153], v[196:199], v[110:113]
	v_mfma_f32_16x16x32_bf16 v[92:95], v[150:153], v[204:207], v[92:95]
	v_mfma_f32_16x16x32_bf16 v[84:87], v[162:165], v[204:207], v[84:87]
	v_mfma_f32_16x16x32_bf16 v[68:71], v[162:165], v[212:215], v[68:71]
	v_mfma_f32_16x16x32_bf16 v[76:79], v[150:153], v[212:215], v[76:79]
	v_mfma_f32_16x16x32_bf16 v[122:125], v[166:169], v[184:187], v[122:125]
	v_mfma_f32_16x16x32_bf16 v[114:117], v[174:177], v[184:187], v[114:117]
	v_mfma_f32_16x16x32_bf16 v[98:101], v[174:177], v[192:195], v[98:101]
	v_mfma_f32_16x16x32_bf16 v[106:109], v[166:169], v[192:195], v[106:109]
	v_mfma_f32_16x16x32_bf16 v[88:91], v[166:169], v[200:203], v[88:91]
	v_mfma_f32_16x16x32_bf16 v[80:83], v[174:177], v[200:203], v[80:83]
	v_mfma_f32_16x16x32_bf16 v[64:67], v[174:177], v[208:211], v[64:67]
	v_mfma_f32_16x16x32_bf16 v[72:75], v[166:169], v[208:211], v[72:75]
	v_mfma_f32_16x16x32_bf16 v[122:125], v[170:173], v[188:191], v[122:125]
	v_mfma_f32_16x16x32_bf16 v[114:117], v[180:183], v[188:191], v[114:117]
	v_mfma_f32_16x16x32_bf16 v[98:101], v[180:183], v[196:199], v[98:101]
	v_mfma_f32_16x16x32_bf16 v[106:109], v[170:173], v[196:199], v[106:109]
	v_mfma_f32_16x16x32_bf16 v[88:91], v[170:173], v[204:207], v[88:91]
	v_mfma_f32_16x16x32_bf16 v[80:83], v[180:183], v[204:207], v[80:83]
	v_mfma_f32_16x16x32_bf16 v[64:67], v[180:183], v[212:215], v[64:67]
	v_mfma_f32_16x16x32_bf16 v[72:75], v[170:173], v[212:215], v[72:75]
	s_barrier
	s_mov_b32 m0, s30
	s_add_u32 s100, s42, 0x80
	s_addc_u32 s101, s43, 0
	s_add_u32 s8, s42, 0x40080
	ds_read_b128 v[184:187], v161 offset:49152
	ds_read_b128 v[188:191], v161 offset:50176
	ds_read_b128 v[192:195], v161 offset:51200
	ds_read_b128 v[196:199], v161 offset:52224
	ds_read_b128 v[200:203], v161 offset:53248
	ds_read_b128 v[204:207], v161 offset:54272
	ds_read_b128 v[208:211], v161 offset:55296
	ds_read_b128 v[212:215], v161 offset:56320
	global_load_lds_dwordx4 v132, s[100:101]
	s_mov_b32 m0, s31
	s_addc_u32 s9, s43, 0
	global_load_lds_dwordx4 v136, s[100:101]
	s_mov_b32 m0, s57
	s_nop 0
	global_load_lds_dwordx4 v132, s[8:9]
	s_mov_b32 m0, s96
	s_nop 0
	global_load_lds_dwordx4 v136, s[8:9]
	s_mov_b32 m0, s11
	s_nop 0
	global_load_lds_dwordx4 v130, s[24:25]
	s_mov_b32 m0, s19
	s_nop 0
	global_load_lds_dwordx4 v134, s[24:25]
	s_waitcnt vmcnt(8)
	s_waitcnt lgkmcnt(0)
	s_barrier
	v_mfma_f32_16x16x32_bf16 v[60:63], v[146:149], v[184:187], v[60:63]
	v_mfma_f32_16x16x32_bf16 v[52:55], v[154:157], v[184:187], v[52:55]
	v_mfma_f32_16x16x32_bf16 v[36:39], v[154:157], v[192:195], v[36:39]
	v_mfma_f32_16x16x32_bf16 v[44:47], v[146:149], v[192:195], v[44:47]
	v_mfma_f32_16x16x32_bf16 v[28:31], v[146:149], v[200:203], v[28:31]
	v_mfma_f32_16x16x32_bf16 v[20:23], v[154:157], v[200:203], v[20:23]
	v_mfma_f32_16x16x32_bf16 v[4:7], v[154:157], v[208:211], v[4:7]
	v_mfma_f32_16x16x32_bf16 v[12:15], v[146:149], v[208:211], v[12:15]
	v_mfma_f32_16x16x32_bf16 v[60:63], v[150:153], v[188:191], v[60:63]
	v_mfma_f32_16x16x32_bf16 v[52:55], v[162:165], v[188:191], v[52:55]
	v_mfma_f32_16x16x32_bf16 v[36:39], v[162:165], v[196:199], v[36:39]
	v_mfma_f32_16x16x32_bf16 v[44:47], v[150:153], v[196:199], v[44:47]
	v_mfma_f32_16x16x32_bf16 v[28:31], v[150:153], v[204:207], v[28:31]
	v_mfma_f32_16x16x32_bf16 v[20:23], v[162:165], v[204:207], v[20:23]
	v_mfma_f32_16x16x32_bf16 v[4:7], v[162:165], v[212:215], v[4:7]
	v_mfma_f32_16x16x32_bf16 v[12:15], v[150:153], v[212:215], v[12:15]
	v_mfma_f32_16x16x32_bf16 v[56:59], v[166:169], v[184:187], v[56:59]
	v_mfma_f32_16x16x32_bf16 v[48:51], v[174:177], v[184:187], v[48:51]
	v_mfma_f32_16x16x32_bf16 v[32:35], v[174:177], v[192:195], v[32:35]
	v_mfma_f32_16x16x32_bf16 v[40:43], v[166:169], v[192:195], v[40:43]
	v_mfma_f32_16x16x32_bf16 v[24:27], v[166:169], v[200:203], v[24:27]
	v_mfma_f32_16x16x32_bf16 v[16:19], v[174:177], v[200:203], v[16:19]
	v_mfma_f32_16x16x32_bf16 v[0:3], v[174:177], v[208:211], v[0:3]
	v_mfma_f32_16x16x32_bf16 v[8:11], v[166:169], v[208:211], v[8:11]
	v_mfma_f32_16x16x32_bf16 v[56:59], v[170:173], v[188:191], v[56:59]
	v_mfma_f32_16x16x32_bf16 v[48:51], v[180:183], v[188:191], v[48:51]
	v_mfma_f32_16x16x32_bf16 v[32:35], v[180:183], v[196:199], v[32:35]
	v_mfma_f32_16x16x32_bf16 v[40:43], v[170:173], v[196:199], v[40:43]
	v_mfma_f32_16x16x32_bf16 v[24:27], v[170:173], v[204:207], v[24:27]
	v_mfma_f32_16x16x32_bf16 v[16:19], v[180:183], v[204:207], v[16:19]
	v_mfma_f32_16x16x32_bf16 v[0:3], v[180:183], v[212:215], v[0:3]
	v_mfma_f32_16x16x32_bf16 v[8:11], v[170:173], v[212:215], v[8:11]
	s_barrier
	s_add_i32 s18, s18, 2
	s_add_u32 s3, s3, 0x100
	s_addc_u32 s2, s2, 0
	s_add_u32 s0, s0, 0x800000
	s_addc_u32 s1, s1, 0
	s_cmp_gt_u32 s18, 13
	s_cbranch_scc0 .LBB0_161
	v_readlane_b32 s0, v255, 45
	v_readlane_b32 s1, v255, 46
	s_and_b64 vcc, exec, s[0:1]
	s_cbranch_vccz .LBB0_164
	s_barrier

; template <class Epi, class Sched, bool ALIGN_EPI = false, bool SP2 = false>
; __device__ __forceinline__ void gemm_phase(PG8_LAS unsigned char* lds, const Gemm g, const Sched& S, const Epi& E) {
;     ...
;         const bool has_next = S.next(ui + 1, nxt);
;         const char* nA = has_next ? (const char*)g.A + (size_t)nxt.pm * tstepA : cA; const char* nB = has_next ? (const char*)g.Bt + (size_t)nxt.pn * tstepB : cB;
;     ...
;         if constexpr (Epi::PEEL) {
;             const char* a1 = cA + kstepA; const char* a2 = cA + 2 * kstepA; const char* b2 = cB + 2 * kstepB; const char* a3 = a2 + kstepA; const char* b3 = b2 + kstepB;
;             PG8_ITER(8);
.LBB0_249:
	s_ashr_i32 s49, s48, 31
	s_lshl_b64 s[2:3], s[48:49], 15
	v_readlane_b32 s11, v255, 15
	s_add_u32 s50, s11, s2
	v_readlane_b32 s2, v255, 16
	s_addc_u32 s51, s2, s3
	s_ashr_i32 s47, s46, 31
	s_lshl_b64 s[2:3], s[46:47], 19
	s_add_u32 s52, s38, s2
	s_addc_u32 s53, s19, s3
	s_add_u32 s28, s42, 0x800000
	s_addc_u32 s29, s43, 0
	s_add_u32 s44, s42, 0xc00000
	s_addc_u32 s45, s43, 0
	s_add_i32 s99, 0, 0x10000
	s_and_b64 s[2:3], s[40:41], exec
	s_cselect_b32 s27, s51, s43
	s_cselect_b32 s47, s50, s42
	s_add_i32 vcc_hi, 0, 0x14000
	v_add_u32_e32 v130, s99, v97
	v_add_u32_e32 v131, vcc_hi, v97
	ds_read_b128 v[0:3], v130
	ds_read_b128 v[4:7], v130 offset:1024
	ds_read_b128 v[8:11], v130 offset:2048
	ds_read_b128 v[12:15], v130 offset:3072
	ds_read_b128 v[16:19], v131
	s_waitcnt lgkmcnt(0)
	ds_read_b128 v[20:23], v131 offset:1024
	ds_read_b128 v[24:27], v131 offset:2048
	ds_read_b128 v[28:31], v131 offset:3072
	s_and_b64 s[2:3], s[40:41], exec
	s_cselect_b32 s49, s53, s25
	s_cselect_b32 s54, s52, s24
	s_add_u32 s2, s42, 0x404000
	s_addc_u32 s3, s43, 0
	s_add_i32 s55, s22, 0xc000
	s_mov_b32 m0, s55
	s_add_i32 s98, s22, 0xe000
	ds_read_b128 v[32:35], v151
	ds_read_b128 v[36:39], v151 offset:1024
	ds_read_b128 v[40:43], v151 offset:2048
	ds_read_b128 v[44:47], v151 offset:3072
	ds_read_b128 v[48:51], v151 offset:4096
	ds_read_b128 v[52:55], v151 offset:5120
	ds_read_b128 v[56:59], v151 offset:6144
	ds_read_b128 v[60:63], v151 offset:7168
	global_load_lds_dwordx4 v134, s[2:3]
	s_mov_b32 m0, s98
	s_nop 0
	global_load_lds_dwordx4 v138, s[2:3]
	s_waitcnt vmcnt(8)
	s_waitcnt lgkmcnt(0)
	s_barrier
	v_mfma_f32_16x16x32_bf16 v[84:87], v[8:11], v[48:51], 0
	v_mfma_f32_16x16x32_bf16 v[88:91], v[12:15], v[52:55], v[84:87]
	v_mfma_f32_16x16x32_bf16 v[84:87], v[0:3], v[56:59], 0
	v_mfma_f32_16x16x32_bf16 v[64:67], v[0:3], v[32:35], 0
	v_mfma_f32_16x16x32_bf16 v[68:71], v[8:11], v[32:35], 0
	v_mfma_f32_16x16x32_bf16 v[72:75], v[0:3], v[40:43], 0
	v_mfma_f32_16x16x32_bf16 v[76:79], v[8:11], v[40:43], 0
	v_mfma_f32_16x16x32_bf16 v[80:83], v[0:3], v[48:51], 0
	v_mfma_f32_16x16x32_bf16 v[92:95], v[4:7], v[60:63], v[84:87]
	v_mfma_f32_16x16x32_bf16 v[84:87], v[8:11], v[56:59], 0
	v_mfma_f32_16x16x32_bf16 v[64:67], v[4:7], v[36:39], v[64:67]
	v_mfma_f32_16x16x32_bf16 v[68:71], v[12:15], v[36:39], v[68:71]
	v_mfma_f32_16x16x32_bf16 v[72:75], v[4:7], v[44:47], v[72:75]
	v_mfma_f32_16x16x32_bf16 v[76:79], v[12:15], v[44:47], v[76:79]
	v_mfma_f32_16x16x32_bf16 v[80:83], v[4:7], v[52:55], v[80:83]
	v_mfma_f32_16x16x32_bf16 v[106:109], v[12:15], v[60:63], v[84:87]
	v_mfma_f32_16x16x32_bf16 v[84:87], v[16:19], v[32:35], 0
	v_mfma_f32_16x16x32_bf16 v[32:35], v[24:27], v[32:35], 0
	v_mfma_f32_16x16x32_bf16 v[110:113], v[20:23], v[36:39], v[84:87]
	v_mfma_f32_16x16x32_bf16 v[32:35], v[28:31], v[36:39], v[32:35]
	v_mfma_f32_16x16x32_bf16 v[36:39], v[16:19], v[40:43], 0
	v_mfma_f32_16x16x32_bf16 v[40:43], v[24:27], v[40:43], 0
	v_mfma_f32_16x16x32_bf16 v[36:39], v[20:23], v[44:47], v[36:39]
	v_mfma_f32_16x16x32_bf16 v[40:43], v[28:31], v[44:47], v[40:43]
	v_mfma_f32_16x16x32_bf16 v[44:47], v[16:19], v[48:51], 0
	v_mfma_f32_16x16x32_bf16 v[48:51], v[24:27], v[48:51], 0
	v_mfma_f32_16x16x32_bf16 v[44:47], v[20:23], v[52:55], v[44:47]
	v_mfma_f32_16x16x32_bf16 v[48:51], v[28:31], v[52:55], v[48:51]
	v_mfma_f32_16x16x32_bf16 v[52:55], v[16:19], v[56:59], 0
	v_mfma_f32_16x16x32_bf16 v[56:59], v[24:27], v[56:59], 0
	v_mfma_f32_16x16x32_bf16 v[52:55], v[20:23], v[60:63], v[52:55]
	v_mfma_f32_16x16x32_bf16 v[56:59], v[28:31], v[60:63], v[56:59]
	s_barrier
	v_lshl_add_u64 v[176:177], s[24:25], 0, v[136:137]
	s_mov_b64 s[2:3], 0x100
	s_add_i32 s99, s99, s10
	v_lshl_add_u64 v[132:133], v[176:177], 0, s[2:3]
	s_mov_b32 m0, s99
	v_lshl_add_u64 v[178:179], s[24:25], 0, v[140:141]
	s_add_i32 vcc_lo, s99, 0x2000
	ds_read_b128 v[60:63], v151 offset:16384
	ds_read_b128 v[84:87], v151 offset:17408
	ds_read_b128 v[98:101], v151 offset:18432
	ds_read_b128 v[102:105], v151 offset:19456
	ds_read_b128 v[114:117], v151 offset:20480
	ds_read_b128 v[118:121], v151 offset:21504
	ds_read_b128 v[122:125], v151 offset:22528
	ds_read_b128 v[126:129], v151 offset:23552
	global_load_lds_dwordx4 v[132:133], off
	v_lshl_add_u64 v[132:133], v[178:179], 0, s[2:3]
	s_add_u32 s2, s24, 0x40100
	s_mov_b32 m0, vcc_lo
	s_addc_u32 s3, s25, 0
	s_add_i32 vcc_hi, vcc_hi, s10
	global_load_lds_dwordx4 v[132:133], off
	s_mov_b32 m0, vcc_hi
	s_add_i32 s30, vcc_hi, 0x2000
	global_load_lds_dwordx4 v136, s[2:3]
	s_mov_b32 m0, s30
	s_mov_b64 s[34:35], 0x100
	global_load_lds_dwordx4 v140, s[2:3]
	s_mov_b32 m0, s22
	s_nop 0
	global_load_lds_dwordx4 v134, s[28:29]
	s_mov_b32 m0, s23
	s_nop 0
	global_load_lds_dwordx4 v138, s[28:29]
	s_waitcnt vmcnt(8)
	s_waitcnt lgkmcnt(0)
	s_barrier
	v_mfma_f32_16x16x32_bf16 v[146:149], v[0:3], v[60:63], 0
	v_mfma_f32_16x16x32_bf16 v[156:159], v[0:3], v[98:101], 0
	v_mfma_f32_16x16x32_bf16 v[164:167], v[0:3], v[114:117], 0
	v_mfma_f32_16x16x32_bf16 v[0:3], v[0:3], v[122:125], 0
	v_mfma_f32_16x16x32_bf16 v[146:149], v[4:7], v[84:87], v[146:149]
	v_mfma_f32_16x16x32_bf16 v[156:159], v[4:7], v[102:105], v[156:159]
	v_mfma_f32_16x16x32_bf16 v[164:167], v[4:7], v[118:121], v[164:167]
	v_mfma_f32_16x16x32_bf16 v[0:3], v[4:7], v[126:129], v[0:3]
	v_mfma_f32_16x16x32_bf16 v[4:7], v[8:11], v[122:125], 0
	v_mfma_f32_16x16x32_bf16 v[152:155], v[8:11], v[60:63], 0
	v_mfma_f32_16x16x32_bf16 v[160:163], v[8:11], v[98:101], 0
	v_mfma_f32_16x16x32_bf16 v[168:171], v[8:11], v[114:117], 0
	v_mfma_f32_16x16x32_bf16 v[8:11], v[12:15], v[126:129], v[4:7]
	v_mfma_f32_16x16x32_bf16 v[152:155], v[12:15], v[84:87], v[152:155]
	v_mfma_f32_16x16x32_bf16 v[160:163], v[12:15], v[102:105], v[160:163]
	v_mfma_f32_16x16x32_bf16 v[168:171], v[12:15], v[118:121], v[168:171]
	v_mfma_f32_16x16x32_bf16 v[4:7], v[16:19], v[60:63], 0
	v_mfma_f32_16x16x32_bf16 v[12:15], v[20:23], v[84:87], v[4:7]
	v_mfma_f32_16x16x32_bf16 v[4:7], v[24:27], v[60:63], 0
	v_mfma_f32_16x16x32_bf16 v[172:175], v[28:31], v[84:87], v[4:7]
	v_mfma_f32_16x16x32_bf16 v[4:7], v[16:19], v[98:101], 0
	v_mfma_f32_16x16x32_bf16 v[180:183], v[20:23], v[102:105], v[4:7]
	v_mfma_f32_16x16x32_bf16 v[4:7], v[24:27], v[98:101], 0
	v_mfma_f32_16x16x32_bf16 v[184:187], v[28:31], v[102:105], v[4:7]
	v_mfma_f32_16x16x32_bf16 v[4:7], v[16:19], v[114:117], 0
	v_mfma_f32_16x16x32_bf16 v[188:191], v[20:23], v[118:121], v[4:7]
	v_mfma_f32_16x16x32_bf16 v[4:7], v[24:27], v[114:117], 0
	v_mfma_f32_16x16x32_bf16 v[192:195], v[28:31], v[118:121], v[4:7]
	v_mfma_f32_16x16x32_bf16 v[4:7], v[16:19], v[122:125], 0
	v_mfma_f32_16x16x32_bf16 v[196:199], v[20:23], v[126:129], v[4:7]
	v_mfma_f32_16x16x32_bf16 v[4:7], v[24:27], v[122:125], 0
	v_mfma_f32_16x16x32_bf16 v[200:203], v[28:31], v[126:129], v[4:7]
	s_barrier
	s_add_i32 s31, 0, 0x18000
	s_add_i32 s13, 0, 0x1c000
	v_add_u32_e32 v132, s31, v97
	v_add_u32_e32 v133, s13, v97
	s_nop 0
	ds_read_b128 v[4:7], v132
	ds_read_b128 v[24:27], v132 offset:1024
	ds_read_b128 v[28:31], v132 offset:2048
	ds_read_b128 v[60:63], v132 offset:3072
	ds_read_b128 v[204:207], v133
	ds_read_b128 v[208:211], v133 offset:1024
	ds_read_b128 v[212:215], v133 offset:2048
	ds_read_b128 v[216:219], v133 offset:3072
	s_add_u32 s2, s42, 0x804000
	s_addc_u32 s3, s43, 0
	s_mov_b32 m0, s39
	ds_read_b128 v[16:19], v151 offset:32768
	ds_read_b128 v[20:23], v151 offset:33792
	ds_read_b128 v[220:223], v151 offset:34816
	ds_read_b128 v[224:227], v151 offset:35840
	ds_read_b128 v[228:231], v151 offset:36864
	ds_read_b128 v[234:237], v151 offset:37888
	ds_read_b128 v[238:241], v151 offset:38912
	ds_read_b128 v[242:245], v151 offset:39936
	global_load_lds_dwordx4 v134, s[2:3]
	s_mov_b32 m0, s56
	s_nop 0
	global_load_lds_dwordx4 v138, s[2:3]
	s_waitcnt vmcnt(8)
	s_waitcnt lgkmcnt(0)
	s_barrier
	v_mfma_f32_16x16x32_bf16 v[64:67], v[4:7], v[16:19], v[64:67]
	v_mfma_f32_16x16x32_bf16 v[118:121], v[24:27], v[20:23], v[64:67]
	v_mfma_f32_16x16x32_bf16 v[64:67], v[28:31], v[16:19], v[68:71]
	v_mfma_f32_16x16x32_bf16 v[114:117], v[60:63], v[20:23], v[64:67]
	v_mfma_f32_16x16x32_bf16 v[64:67], v[4:7], v[220:223], v[72:75]
	v_mfma_f32_16x16x32_bf16 v[102:105], v[24:27], v[224:227], v[64:67]
	v_mfma_f32_16x16x32_bf16 v[64:67], v[28:31], v[220:223], v[76:79]
	v_mfma_f32_16x16x32_bf16 v[98:101], v[60:63], v[224:227], v[64:67]
	v_mfma_f32_16x16x32_bf16 v[64:67], v[4:7], v[228:231], v[80:83]
	v_mfma_f32_16x16x32_bf16 v[84:87], v[24:27], v[234:237], v[64:67]
	v_mfma_f32_16x16x32_bf16 v[64:67], v[28:31], v[228:231], v[88:91]
	v_mfma_f32_16x16x32_bf16 v[80:83], v[60:63], v[234:237], v[64:67]
	v_mfma_f32_16x16x32_bf16 v[64:67], v[4:7], v[238:241], v[92:95]
	v_mfma_f32_16x16x32_bf16 v[68:71], v[24:27], v[242:245], v[64:67]
	v_mfma_f32_16x16x32_bf16 v[64:67], v[28:31], v[238:241], v[106:109]
	v_mfma_f32_16x16x32_bf16 v[64:67], v[60:63], v[242:245], v[64:67]
	v_mfma_f32_16x16x32_bf16 v[72:75], v[204:207], v[16:19], v[110:113]
	v_mfma_f32_16x16x32_bf16 v[16:19], v[212:215], v[16:19], v[32:35]
	v_mfma_f32_16x16x32_bf16 v[122:125], v[216:219], v[20:23], v[16:19]
	v_mfma_f32_16x16x32_bf16 v[16:19], v[204:207], v[220:223], v[36:39]
	v_mfma_f32_16x16x32_bf16 v[110:113], v[208:211], v[224:227], v[16:19]
	v_mfma_f32_16x16x32_bf16 v[16:19], v[212:215], v[220:223], v[40:43]
	v_mfma_f32_16x16x32_bf16 v[106:109], v[216:219], v[224:227], v[16:19]
	v_mfma_f32_16x16x32_bf16 v[16:19], v[204:207], v[228:231], v[44:47]
	v_mfma_f32_16x16x32_bf16 v[92:95], v[208:211], v[234:237], v[16:19]
	v_mfma_f32_16x16x32_bf16 v[16:19], v[212:215], v[228:231], v[48:51]
	v_mfma_f32_16x16x32_bf16 v[88:91], v[216:219], v[234:237], v[16:19]
	v_mfma_f32_16x16x32_bf16 v[16:19], v[204:207], v[238:241], v[52:55]
	v_mfma_f32_16x16x32_bf16 v[76:79], v[208:211], v[242:245], v[16:19]
	v_mfma_f32_16x16x32_bf16 v[16:19], v[212:215], v[238:241], v[56:59]
	v_mfma_f32_16x16x32_bf16 v[126:129], v[208:211], v[20:23], v[72:75]
	v_mfma_f32_16x16x32_bf16 v[72:75], v[216:219], v[242:245], v[16:19]
	s_barrier
; template <class Epi, class Sched, bool ALIGN_EPI = false, bool SP2 = false>
; __device__ __forceinline__ void gemm_phase(PG8_LAS unsigned char* lds, const Gemm g, const Sched& S, const Epi& E) {
;     ...
;         if constexpr (Epi::PEEL) {
;             const char* a1 = cA + kstepA; const char* a2 = cA + 2 * kstepA; const char* b2 = cB + 2 * kstepB; const char* a3 = a2 + kstepA; const char* b3 = b2 + kstepB;
;             PG8_ITER(8);
;         }
;         for (int t = (Epi::PEEL ? 2 : 0); t < nt; t += 2) {
;             const bool last = (t == nt - 2);
;             const char* a1 = cA + (size_t)(t + 1) * kstepA;
;             const char* a2 = last ? nA : cA + (size_t)(t + 2) * kstepA; const char* b2 = last ? nB : cB + (size_t)(t + 2) * kstepB;
;             const char* a3 = a2 + kstepA; const char* b3 = b2 + kstepB;
;             PG8_ITER(8);
	s_mov_b64 s[2:3], 0x180
	s_add_i32 s31, s31, s10
	s_nop 1
	v_lshl_add_u64 v[16:17], v[176:177], 0, s[2:3]
	s_mov_b32 m0, s31
	s_add_i32 s12, s31, 0x2000
	ds_read_b128 v[40:43], v151 offset:49152
	ds_read_b128 v[44:47], v151 offset:50176
	ds_read_b128 v[220:223], v151 offset:51200
	ds_read_b128 v[224:227], v151 offset:52224
	ds_read_b128 v[228:231], v151 offset:53248
	ds_read_b128 v[234:237], v151 offset:54272
	ds_read_b128 v[238:241], v151 offset:55296
	ds_read_b128 v[242:245], v151 offset:56320
	global_load_lds_dwordx4 v[16:17], off
	v_lshl_add_u64 v[16:17], v[178:179], 0, s[2:3]
	s_add_u32 s2, s24, 0x40180
	s_mov_b32 m0, s12
	s_addc_u32 s3, s25, 0
	s_add_i32 s13, s13, s10
	global_load_lds_dwordx4 v[16:17], off
	s_mov_b32 m0, s13
	s_add_i32 s11, s13, 0x2000
	global_load_lds_dwordx4 v136, s[2:3]
	s_mov_b32 m0, s11
	s_nop 0
	global_load_lds_dwordx4 v140, s[2:3]
	s_mov_b32 m0, s59
	s_nop 0
	global_load_lds_dwordx4 v134, s[44:45]
	s_mov_b32 m0, s96
	s_nop 0
	global_load_lds_dwordx4 v138, s[44:45]
	s_waitcnt vmcnt(8)
	s_waitcnt lgkmcnt(0)
	s_barrier
	v_mfma_f32_16x16x32_bf16 v[16:19], v[4:7], v[40:43], v[146:149]
	v_mfma_f32_16x16x32_bf16 v[52:55], v[24:27], v[44:47], v[16:19]
	v_mfma_f32_16x16x32_bf16 v[16:19], v[28:31], v[40:43], v[152:155]
	v_mfma_f32_16x16x32_bf16 v[48:51], v[60:63], v[44:47], v[16:19]
	v_mfma_f32_16x16x32_bf16 v[16:19], v[4:7], v[220:223], v[156:159]
	v_mfma_f32_16x16x32_bf16 v[36:39], v[24:27], v[224:227], v[16:19]
	v_mfma_f32_16x16x32_bf16 v[16:19], v[28:31], v[220:223], v[160:163]
	v_mfma_f32_16x16x32_bf16 v[32:35], v[60:63], v[224:227], v[16:19]
	v_mfma_f32_16x16x32_bf16 v[16:19], v[4:7], v[228:231], v[164:167]
	v_mfma_f32_16x16x32_bf16 v[0:3], v[4:7], v[238:241], v[0:3]
	v_mfma_f32_16x16x32_bf16 v[20:23], v[24:27], v[234:237], v[16:19]
	v_mfma_f32_16x16x32_bf16 v[16:19], v[28:31], v[228:231], v[168:171]
	v_mfma_f32_16x16x32_bf16 v[4:7], v[24:27], v[242:245], v[0:3]
	v_mfma_f32_16x16x32_bf16 v[0:3], v[28:31], v[238:241], v[8:11]
	v_mfma_f32_16x16x32_bf16 v[16:19], v[60:63], v[234:237], v[16:19]
	v_mfma_f32_16x16x32_bf16 v[0:3], v[60:63], v[242:245], v[0:3]
	v_mfma_f32_16x16x32_bf16 v[8:11], v[204:207], v[40:43], v[12:15]
	v_mfma_f32_16x16x32_bf16 v[60:63], v[208:211], v[44:47], v[8:11]
	v_mfma_f32_16x16x32_bf16 v[8:11], v[212:215], v[40:43], v[172:175]
	v_mfma_f32_16x16x32_bf16 v[56:59], v[216:219], v[44:47], v[8:11]
	v_mfma_f32_16x16x32_bf16 v[8:11], v[204:207], v[220:223], v[180:183]
	v_mfma_f32_16x16x32_bf16 v[44:47], v[208:211], v[224:227], v[8:11]
	v_mfma_f32_16x16x32_bf16 v[8:11], v[212:215], v[220:223], v[184:187]
	v_mfma_f32_16x16x32_bf16 v[40:43], v[216:219], v[224:227], v[8:11]
	v_mfma_f32_16x16x32_bf16 v[8:11], v[204:207], v[228:231], v[188:191]
	v_mfma_f32_16x16x32_bf16 v[28:31], v[208:211], v[234:237], v[8:11]
	v_mfma_f32_16x16x32_bf16 v[8:11], v[212:215], v[228:231], v[192:195]
	v_mfma_f32_16x16x32_bf16 v[24:27], v[216:219], v[234:237], v[8:11]
	v_mfma_f32_16x16x32_bf16 v[8:11], v[204:207], v[238:241], v[196:199]
	v_mfma_f32_16x16x32_bf16 v[12:15], v[208:211], v[242:245], v[8:11]
	v_mfma_f32_16x16x32_bf16 v[8:11], v[212:215], v[238:241], v[200:203]
	v_mfma_f32_16x16x32_bf16 v[8:11], v[216:219], v[242:245], v[8:11]
	s_barrier
	s_add_u32 s3, s24, 0x200
	s_addc_u32 s2, s25, 0
	s_add_u32 s24, s42, 0xc04000
	s_addc_u32 s25, s43, 0
	s_mov_b32 s18, 0
.LBB0_250:
	ds_read_b128 v[146:149], v130
	ds_read_b128 v[152:155], v130 offset:1024
	ds_read_b128 v[156:159], v130 offset:2048
	ds_read_b128 v[160:163], v130 offset:3072
	ds_read_b128 v[164:167], v131
	ds_read_b128 v[168:171], v131 offset:1024
	ds_read_b128 v[172:175], v131 offset:2048
	ds_read_b128 v[180:183], v131 offset:3072
	s_add_u32 s16, s24, 0x3fc000
	s_addc_u32 s17, s25, 0
	s_cmp_eq_u32 s18, 12
	s_cselect_b32 s28, s47, s16
	s_cselect_b32 s29, s27, s17
	s_cselect_b32 s44, s54, s3
	s_cselect_b32 s45, s49, s2
	s_add_u32 s42, s28, 0x400000
	s_addc_u32 s43, s29, 0
	s_mov_b32 m0, s55
	ds_read_b128 v[184:187], v151
	ds_read_b128 v[188:191], v151 offset:1024
	ds_read_b128 v[192:195], v151 offset:2048
	ds_read_b128 v[196:199], v151 offset:3072
	ds_read_b128 v[200:203], v151 offset:4096
	ds_read_b128 v[204:207], v151 offset:5120
	ds_read_b128 v[208:211], v151 offset:6144
	ds_read_b128 v[212:215], v151 offset:7168
	global_load_lds_dwordx4 v144, s[24:25]
	s_mov_b32 m0, s98
	s_nop 0
	global_load_lds_dwordx4 v142, s[24:25]
	s_waitcnt vmcnt(8)
	s_waitcnt lgkmcnt(0)
	s_barrier
	v_mfma_f32_16x16x32_bf16 v[118:121], v[146:149], v[184:187], v[118:121]
	v_mfma_f32_16x16x32_bf16 v[114:117], v[156:159], v[184:187], v[114:117]
	v_mfma_f32_16x16x32_bf16 v[98:101], v[156:159], v[192:195], v[98:101]
	v_mfma_f32_16x16x32_bf16 v[102:105], v[146:149], v[192:195], v[102:105]
	v_mfma_f32_16x16x32_bf16 v[84:87], v[146:149], v[200:203], v[84:87]
	v_mfma_f32_16x16x32_bf16 v[80:83], v[156:159], v[200:203], v[80:83]
	v_mfma_f32_16x16x32_bf16 v[64:67], v[156:159], v[208:211], v[64:67]
	v_mfma_f32_16x16x32_bf16 v[68:71], v[146:149], v[208:211], v[68:71]
	v_mfma_f32_16x16x32_bf16 v[118:121], v[152:155], v[188:191], v[118:121]
	v_mfma_f32_16x16x32_bf16 v[114:117], v[160:163], v[188:191], v[114:117]
	v_mfma_f32_16x16x32_bf16 v[98:101], v[160:163], v[196:199], v[98:101]
	v_mfma_f32_16x16x32_bf16 v[102:105], v[152:155], v[196:199], v[102:105]
	v_mfma_f32_16x16x32_bf16 v[84:87], v[152:155], v[204:207], v[84:87]
	v_mfma_f32_16x16x32_bf16 v[80:83], v[160:163], v[204:207], v[80:83]
	v_mfma_f32_16x16x32_bf16 v[64:67], v[160:163], v[212:215], v[64:67]
	v_mfma_f32_16x16x32_bf16 v[68:71], v[152:155], v[212:215], v[68:71]
	v_mfma_f32_16x16x32_bf16 v[126:129], v[164:167], v[184:187], v[126:129]
	v_mfma_f32_16x16x32_bf16 v[122:125], v[172:175], v[184:187], v[122:125]
	v_mfma_f32_16x16x32_bf16 v[106:109], v[172:175], v[192:195], v[106:109]
	v_mfma_f32_16x16x32_bf16 v[110:113], v[164:167], v[192:195], v[110:113]
	v_mfma_f32_16x16x32_bf16 v[92:95], v[164:167], v[200:203], v[92:95]
	v_mfma_f32_16x16x32_bf16 v[88:91], v[172:175], v[200:203], v[88:91]
	v_mfma_f32_16x16x32_bf16 v[72:75], v[172:175], v[208:211], v[72:75]
	v_mfma_f32_16x16x32_bf16 v[76:79], v[164:167], v[208:211], v[76:79]
	v_mfma_f32_16x16x32_bf16 v[126:129], v[168:171], v[188:191], v[126:129]
	v_mfma_f32_16x16x32_bf16 v[122:125], v[180:183], v[188:191], v[122:125]
	v_mfma_f32_16x16x32_bf16 v[106:109], v[180:183], v[196:199], v[106:109]
	v_mfma_f32_16x16x32_bf16 v[110:113], v[168:171], v[196:199], v[110:113]
	v_mfma_f32_16x16x32_bf16 v[92:95], v[168:171], v[204:207], v[92:95]
	v_mfma_f32_16x16x32_bf16 v[88:91], v[180:183], v[204:207], v[88:91]
	v_mfma_f32_16x16x32_bf16 v[72:75], v[180:183], v[212:215], v[72:75]
	v_mfma_f32_16x16x32_bf16 v[76:79], v[168:171], v[212:215], v[76:79]
	s_barrier
	s_mov_b32 m0, s99
	s_add_u32 s16, s44, 0x40000
	ds_read_b128 v[184:187], v151 offset:16384
	ds_read_b128 v[188:191], v151 offset:17408
	ds_read_b128 v[192:195], v151 offset:18432
	ds_read_b128 v[196:199], v151 offset:19456
	ds_read_b128 v[200:203], v151 offset:20480
	ds_read_b128 v[204:207], v151 offset:21504
	ds_read_b128 v[208:211], v151 offset:22528
	ds_read_b128 v[212:215], v151 offset:23552
	global_load_lds_dwordx4 v136, s[44:45]
	s_mov_b32 m0, vcc_lo
	s_addc_u32 s17, s45, 0
	global_load_lds_dwordx4 v140, s[44:45]
	s_mov_b32 m0, vcc_hi
	s_nop 0
	global_load_lds_dwordx4 v136, s[16:17]
	s_mov_b32 m0, s30
	s_nop 0
	global_load_lds_dwordx4 v140, s[16:17]
	s_mov_b32 m0, s22
	s_nop 0
	global_load_lds_dwordx4 v134, s[28:29]
	s_mov_b32 m0, s23
	s_nop 0
	global_load_lds_dwordx4 v138, s[28:29]
	s_waitcnt vmcnt(8)
	s_waitcnt lgkmcnt(0)
	s_barrier
	v_mfma_f32_16x16x32_bf16 v[52:55], v[146:149], v[184:187], v[52:55]
	v_mfma_f32_16x16x32_bf16 v[48:51], v[156:159], v[184:187], v[48:51]
	v_mfma_f32_16x16x32_bf16 v[32:35], v[156:159], v[192:195], v[32:35]
	v_mfma_f32_16x16x32_bf16 v[36:39], v[146:149], v[192:195], v[36:39]
	v_mfma_f32_16x16x32_bf16 v[20:23], v[146:149], v[200:203], v[20:23]
	v_mfma_f32_16x16x32_bf16 v[16:19], v[156:159], v[200:203], v[16:19]
	v_mfma_f32_16x16x32_bf16 v[0:3], v[156:159], v[208:211], v[0:3]
	v_mfma_f32_16x16x32_bf16 v[4:7], v[146:149], v[208:211], v[4:7]
	v_mfma_f32_16x16x32_bf16 v[52:55], v[152:155], v[188:191], v[52:55]
	v_mfma_f32_16x16x32_bf16 v[48:51], v[160:163], v[188:191], v[48:51]
	v_mfma_f32_16x16x32_bf16 v[32:35], v[160:163], v[196:199], v[32:35]
	v_mfma_f32_16x16x32_bf16 v[36:39], v[152:155], v[196:199], v[36:39]
	v_mfma_f32_16x16x32_bf16 v[20:23], v[152:155], v[204:207], v[20:23]
	v_mfma_f32_16x16x32_bf16 v[16:19], v[160:163], v[204:207], v[16:19]
	v_mfma_f32_16x16x32_bf16 v[0:3], v[160:163], v[212:215], v[0:3]
	v_mfma_f32_16x16x32_bf16 v[4:7], v[152:155], v[212:215], v[4:7]
	v_mfma_f32_16x16x32_bf16 v[60:63], v[164:167], v[184:187], v[60:63]
	v_mfma_f32_16x16x32_bf16 v[56:59], v[172:175], v[184:187], v[56:59]
	v_mfma_f32_16x16x32_bf16 v[40:43], v[172:175], v[192:195], v[40:43]
	v_mfma_f32_16x16x32_bf16 v[44:47], v[164:167], v[192:195], v[44:47]
	v_mfma_f32_16x16x32_bf16 v[28:31], v[164:167], v[200:203], v[28:31]
	v_mfma_f32_16x16x32_bf16 v[24:27], v[172:175], v[200:203], v[24:27]
	v_mfma_f32_16x16x32_bf16 v[8:11], v[172:175], v[208:211], v[8:11]
	v_mfma_f32_16x16x32_bf16 v[12:15], v[164:167], v[208:211], v[12:15]
	v_mfma_f32_16x16x32_bf16 v[60:63], v[168:171], v[188:191], v[60:63]
	v_mfma_f32_16x16x32_bf16 v[56:59], v[180:183], v[188:191], v[56:59]
	v_mfma_f32_16x16x32_bf16 v[40:43], v[180:183], v[196:199], v[40:43]
	v_mfma_f32_16x16x32_bf16 v[44:47], v[168:171], v[196:199], v[44:47]
	v_mfma_f32_16x16x32_bf16 v[28:31], v[168:171], v[204:207], v[28:31]
	v_mfma_f32_16x16x32_bf16 v[24:27], v[180:183], v[204:207], v[24:27]
	v_mfma_f32_16x16x32_bf16 v[8:11], v[180:183], v[212:215], v[8:11]
	v_mfma_f32_16x16x32_bf16 v[12:15], v[168:171], v[212:215], v[12:15]
	s_barrier
	ds_read_b128 v[146:149], v132
	ds_read_b128 v[152:155], v132 offset:1024
	ds_read_b128 v[156:159], v132 offset:2048
	ds_read_b128 v[160:163], v132 offset:3072
	ds_read_b128 v[164:167], v133
	ds_read_b128 v[168:171], v133 offset:1024
	ds_read_b128 v[172:175], v133 offset:2048
	ds_read_b128 v[180:183], v133 offset:3072
	s_add_u32 s16, s28, 0x4000
	s_addc_u32 s17, s29, 0
	s_mov_b32 m0, s39
	ds_read_b128 v[184:187], v151 offset:32768
	ds_read_b128 v[188:191], v151 offset:33792
	ds_read_b128 v[192:195], v151 offset:34816
	ds_read_b128 v[196:199], v151 offset:35840
	ds_read_b128 v[200:203], v151 offset:36864
	ds_read_b128 v[204:207], v151 offset:37888
	ds_read_b128 v[208:211], v151 offset:38912
	ds_read_b128 v[212:215], v151 offset:39936
	global_load_lds_dwordx4 v134, s[16:17]
	s_mov_b32 m0, s56
	s_nop 0
	global_load_lds_dwordx4 v138, s[16:17]
	s_waitcnt vmcnt(8)
	s_waitcnt lgkmcnt(0)
	s_barrier
; #define PG8_BAR __builtin_amdgcn_s_barrier()
; template <class Epi, class Sched, bool ALIGN_EPI = false, bool SP2 = false>
; __device__ __forceinline__ void gemm_phase(PG8_LAS unsigned char* lds, const Gemm g, const Sched& S, const Epi& E) {
;     ...
;         if constexpr (Epi::PEEL) {
;             const char* a1 = cA + kstepA; const char* a2 = cA + 2 * kstepA; const char* b2 = cB + 2 * kstepB; const char* a3 = a2 + kstepA; const char* b3 = b2 + kstepB;
;             PG8_ITER(8);
;         }
;         for (int t = (Epi::PEEL ? 2 : 0); t < nt; t += 2) {
;             const bool last = (t == nt - 2);
;             const char* a1 = cA + (size_t)(t + 1) * kstepA;
;             const char* a2 = last ? nA : cA + (size_t)(t + 2) * kstepA; const char* b2 = last ? nB : cB + (size_t)(t + 2) * kstepB;
;             const char* a3 = a2 + kstepA; const char* b3 = b2 + kstepB;
;             PG8_ITER(8);
;         }
;     ...
;         if constexpr (ALIGN_EPI) { if (wr == 0) PG8_BAR; }
	v_mfma_f32_16x16x32_bf16 v[118:121], v[146:149], v[184:187], v[118:121]
	v_mfma_f32_16x16x32_bf16 v[114:117], v[156:159], v[184:187], v[114:117]
	v_mfma_f32_16x16x32_bf16 v[98:101], v[156:159], v[192:195], v[98:101]
	v_mfma_f32_16x16x32_bf16 v[102:105], v[146:149], v[192:195], v[102:105]
	v_mfma_f32_16x16x32_bf16 v[84:87], v[146:149], v[200:203], v[84:87]
	v_mfma_f32_16x16x32_bf16 v[80:83], v[156:159], v[200:203], v[80:83]
	v_mfma_f32_16x16x32_bf16 v[64:67], v[156:159], v[208:211], v[64:67]
	v_mfma_f32_16x16x32_bf16 v[68:71], v[146:149], v[208:211], v[68:71]
	v_mfma_f32_16x16x32_bf16 v[118:121], v[152:155], v[188:191], v[118:121]
	v_mfma_f32_16x16x32_bf16 v[114:117], v[160:163], v[188:191], v[114:117]
	v_mfma_f32_16x16x32_bf16 v[98:101], v[160:163], v[196:199], v[98:101]
	v_mfma_f32_16x16x32_bf16 v[102:105], v[152:155], v[196:199], v[102:105]
	v_mfma_f32_16x16x32_bf16 v[84:87], v[152:155], v[204:207], v[84:87]
	v_mfma_f32_16x16x32_bf16 v[80:83], v[160:163], v[204:207], v[80:83]
	v_mfma_f32_16x16x32_bf16 v[64:67], v[160:163], v[212:215], v[64:67]
	v_mfma_f32_16x16x32_bf16 v[68:71], v[152:155], v[212:215], v[68:71]
	v_mfma_f32_16x16x32_bf16 v[126:129], v[164:167], v[184:187], v[126:129]
	v_mfma_f32_16x16x32_bf16 v[122:125], v[172:175], v[184:187], v[122:125]
	v_mfma_f32_16x16x32_bf16 v[106:109], v[172:175], v[192:195], v[106:109]
	v_mfma_f32_16x16x32_bf16 v[110:113], v[164:167], v[192:195], v[110:113]
	v_mfma_f32_16x16x32_bf16 v[92:95], v[164:167], v[200:203], v[92:95]
	v_mfma_f32_16x16x32_bf16 v[88:91], v[172:175], v[200:203], v[88:91]
	v_mfma_f32_16x16x32_bf16 v[72:75], v[172:175], v[208:211], v[72:75]
	v_mfma_f32_16x16x32_bf16 v[76:79], v[164:167], v[208:211], v[76:79]
	v_mfma_f32_16x16x32_bf16 v[126:129], v[168:171], v[188:191], v[126:129]
	v_mfma_f32_16x16x32_bf16 v[122:125], v[180:183], v[188:191], v[122:125]
	v_mfma_f32_16x16x32_bf16 v[106:109], v[180:183], v[196:199], v[106:109]
	v_mfma_f32_16x16x32_bf16 v[110:113], v[168:171], v[196:199], v[110:113]
	v_mfma_f32_16x16x32_bf16 v[92:95], v[168:171], v[204:207], v[92:95]
	v_mfma_f32_16x16x32_bf16 v[88:91], v[180:183], v[204:207], v[88:91]
	v_mfma_f32_16x16x32_bf16 v[72:75], v[180:183], v[212:215], v[72:75]
	v_mfma_f32_16x16x32_bf16 v[76:79], v[168:171], v[212:215], v[76:79]
	s_barrier
	s_mov_b32 m0, s31
	s_add_u32 s100, s44, 0x80
	s_addc_u32 s101, s45, 0
	s_add_u32 s16, s44, 0x40080
	ds_read_b128 v[184:187], v151 offset:49152
	ds_read_b128 v[188:191], v151 offset:50176
	ds_read_b128 v[192:195], v151 offset:51200
	ds_read_b128 v[196:199], v151 offset:52224
	ds_read_b128 v[200:203], v151 offset:53248
	ds_read_b128 v[204:207], v151 offset:54272
	ds_read_b128 v[208:211], v151 offset:55296
	ds_read_b128 v[212:215], v151 offset:56320
	global_load_lds_dwordx4 v136, s[100:101]
	s_mov_b32 m0, s12
	s_addc_u32 s17, s45, 0
	global_load_lds_dwordx4 v140, s[100:101]
	s_mov_b32 m0, s13
	s_nop 0
	global_load_lds_dwordx4 v136, s[16:17]
	s_mov_b32 m0, s11
	s_nop 0
	global_load_lds_dwordx4 v140, s[16:17]
	s_mov_b32 m0, s59
	s_nop 0
	global_load_lds_dwordx4 v134, s[42:43]
	s_mov_b32 m0, s96
	s_nop 0
	global_load_lds_dwordx4 v138, s[42:43]
	s_waitcnt vmcnt(8)
	s_waitcnt lgkmcnt(0)
	s_barrier
	v_mfma_f32_16x16x32_bf16 v[52:55], v[146:149], v[184:187], v[52:55]
	v_mfma_f32_16x16x32_bf16 v[48:51], v[156:159], v[184:187], v[48:51]
	v_mfma_f32_16x16x32_bf16 v[32:35], v[156:159], v[192:195], v[32:35]
	v_mfma_f32_16x16x32_bf16 v[36:39], v[146:149], v[192:195], v[36:39]
	v_mfma_f32_16x16x32_bf16 v[20:23], v[146:149], v[200:203], v[20:23]
	v_mfma_f32_16x16x32_bf16 v[16:19], v[156:159], v[200:203], v[16:19]
	v_mfma_f32_16x16x32_bf16 v[0:3], v[156:159], v[208:211], v[0:3]
	v_mfma_f32_16x16x32_bf16 v[4:7], v[146:149], v[208:211], v[4:7]
	v_mfma_f32_16x16x32_bf16 v[52:55], v[152:155], v[188:191], v[52:55]
	v_mfma_f32_16x16x32_bf16 v[48:51], v[160:163], v[188:191], v[48:51]
	v_mfma_f32_16x16x32_bf16 v[32:35], v[160:163], v[196:199], v[32:35]
	v_mfma_f32_16x16x32_bf16 v[36:39], v[152:155], v[196:199], v[36:39]
	v_mfma_f32_16x16x32_bf16 v[20:23], v[152:155], v[204:207], v[20:23]
	v_mfma_f32_16x16x32_bf16 v[16:19], v[160:163], v[204:207], v[16:19]
	v_mfma_f32_16x16x32_bf16 v[0:3], v[160:163], v[212:215], v[0:3]
	v_mfma_f32_16x16x32_bf16 v[4:7], v[152:155], v[212:215], v[4:7]
	v_mfma_f32_16x16x32_bf16 v[60:63], v[164:167], v[184:187], v[60:63]
	v_mfma_f32_16x16x32_bf16 v[56:59], v[172:175], v[184:187], v[56:59]
	v_mfma_f32_16x16x32_bf16 v[40:43], v[172:175], v[192:195], v[40:43]
	v_mfma_f32_16x16x32_bf16 v[44:47], v[164:167], v[192:195], v[44:47]
	v_mfma_f32_16x16x32_bf16 v[28:31], v[164:167], v[200:203], v[28:31]
	v_mfma_f32_16x16x32_bf16 v[24:27], v[172:175], v[200:203], v[24:27]
	v_mfma_f32_16x16x32_bf16 v[8:11], v[172:175], v[208:211], v[8:11]
	v_mfma_f32_16x16x32_bf16 v[12:15], v[164:167], v[208:211], v[12:15]
	v_mfma_f32_16x16x32_bf16 v[60:63], v[168:171], v[188:191], v[60:63]
	v_mfma_f32_16x16x32_bf16 v[56:59], v[180:183], v[188:191], v[56:59]
	v_mfma_f32_16x16x32_bf16 v[40:43], v[180:183], v[196:199], v[40:43]
	v_mfma_f32_16x16x32_bf16 v[44:47], v[168:171], v[196:199], v[44:47]
	v_mfma_f32_16x16x32_bf16 v[28:31], v[168:171], v[204:207], v[28:31]
	v_mfma_f32_16x16x32_bf16 v[24:27], v[180:183], v[204:207], v[24:27]
	v_mfma_f32_16x16x32_bf16 v[8:11], v[180:183], v[212:215], v[8:11]
	v_mfma_f32_16x16x32_bf16 v[12:15], v[168:171], v[212:215], v[12:15]
	s_barrier
	s_add_i32 s18, s18, 2
	s_add_u32 s3, s3, 0x100
	s_addc_u32 s2, s2, 0
	s_add_u32 s24, s24, 0x800000
	s_addc_u32 s25, s25, 0
	s_cmp_gt_u32 s18, 13
	s_cbranch_scc0 .LBB0_250
	v_readlane_b32 s2, v255, 33
	v_readlane_b32 s3, v255, 34
	v_readlane_b32 s12, v255, 31
	s_and_b64 vcc, exec, s[2:3]
	v_readlane_b32 s13, v255, 32
	s_cbranch_vccz .LBB0_253
	s_barrier

; template <class Epi, class Sched, bool ALIGN_EPI = false, bool SP2 = false>
; __device__ __forceinline__ void gemm_phase(PG8_LAS unsigned char* lds, const Gemm g, const Sched& S, const Epi& E) {
;     ...
;         for (int t = (Epi::PEEL ? 2 : 0); t < nt; t += 2) {
;             const bool last = (t == nt - 2);
;             const char* a1 = cA + (size_t)(t + 1) * kstepA;
;             const char* a2 = last ? nA : cA + (size_t)(t + 2) * kstepA; const char* b2 = last ? nB : cB + (size_t)(t + 2) * kstepB;
;             const char* a3 = a2 + kstepA; const char* b3 = b2 + kstepB;
.LBB0_345:
	s_add_i32 s10, s10, 2
	s_add_u32 s44, s42, s34
	s_addc_u32 s45, s43, s35
	s_add_i32 s18, 0, 0x10000
	s_and_b64 s[2:3], exec, s[46:47]
	s_cselect_b32 s3, s13, s59
	s_cselect_b32 s2, s12, s58
	s_add_i32 s38, 0, 0x14000
	v_add_u32_e32 v142, s18, v97
	v_add_u32_e32 v170, s38, v97
	ds_read_b128 v[122:125], v142
	ds_read_b128 v[126:129], v142 offset:1024
	ds_read_b128 v[138:141], v142 offset:2048
	ds_read_b128 v[142:145], v142 offset:3072
	ds_read_b128 v[146:149], v170
	ds_read_b128 v[150:153], v170 offset:1024
	ds_read_b128 v[154:157], v170 offset:2048
	ds_read_b128 v[170:173], v170 offset:3072
	s_add_i32 m0, s97, 0xc000
	ds_read_b128 v[174:177], v188
	ds_read_b128 v[180:183], v188 offset:1024
	ds_read_b128 v[184:187], v188 offset:2048
	ds_read_b128 v[190:193], v188 offset:3072
	ds_read_b128 v[194:197], v188 offset:4096
	ds_read_b128 v[198:201], v188 offset:5120
	ds_read_b128 v[202:205], v188 offset:6144
	ds_read_b128 v[206:209], v188 offset:7168
	global_load_lds_dwordx4 v168, s[24:25]
	s_add_i32 m0, s97, 0xe000
	s_nop 0
	global_load_lds_dwordx4 v166, s[24:25]
	s_waitcnt vmcnt(8)
	s_waitcnt lgkmcnt(0)
	s_barrier
	v_mfma_f32_16x16x32_bf16 v[134:137], v[122:125], v[174:177], v[134:137]
	v_mfma_f32_16x16x32_bf16 v[130:133], v[138:141], v[174:177], v[130:133]
	v_mfma_f32_16x16x32_bf16 v[106:109], v[138:141], v[184:187], v[106:109]
	v_mfma_f32_16x16x32_bf16 v[110:113], v[122:125], v[184:187], v[110:113]
	v_mfma_f32_16x16x32_bf16 v[92:95], v[122:125], v[194:197], v[92:95]
	v_mfma_f32_16x16x32_bf16 v[88:91], v[138:141], v[194:197], v[88:91]
	v_mfma_f32_16x16x32_bf16 v[72:75], v[138:141], v[202:205], v[72:75]
	v_mfma_f32_16x16x32_bf16 v[76:79], v[122:125], v[202:205], v[76:79]
	v_mfma_f32_16x16x32_bf16 v[134:137], v[126:129], v[180:183], v[134:137]
	v_mfma_f32_16x16x32_bf16 v[130:133], v[142:145], v[180:183], v[130:133]
	v_mfma_f32_16x16x32_bf16 v[106:109], v[142:145], v[190:193], v[106:109]
	v_mfma_f32_16x16x32_bf16 v[110:113], v[126:129], v[190:193], v[110:113]
	v_mfma_f32_16x16x32_bf16 v[92:95], v[126:129], v[198:201], v[92:95]
	v_mfma_f32_16x16x32_bf16 v[88:91], v[142:145], v[198:201], v[88:91]
	v_mfma_f32_16x16x32_bf16 v[72:75], v[142:145], v[206:209], v[72:75]
	v_mfma_f32_16x16x32_bf16 v[76:79], v[126:129], v[206:209], v[76:79]
	v_mfma_f32_16x16x32_bf16 v[118:121], v[146:149], v[174:177], v[118:121]
	v_mfma_f32_16x16x32_bf16 v[114:117], v[154:157], v[174:177], v[114:117]
	v_mfma_f32_16x16x32_bf16 v[98:101], v[154:157], v[184:187], v[98:101]
	v_mfma_f32_16x16x32_bf16 v[102:105], v[146:149], v[184:187], v[102:105]
	v_mfma_f32_16x16x32_bf16 v[84:87], v[146:149], v[194:197], v[84:87]
	v_mfma_f32_16x16x32_bf16 v[80:83], v[154:157], v[194:197], v[80:83]
	v_mfma_f32_16x16x32_bf16 v[64:67], v[154:157], v[202:205], v[64:67]
	v_mfma_f32_16x16x32_bf16 v[68:71], v[146:149], v[202:205], v[68:71]
	v_mfma_f32_16x16x32_bf16 v[118:121], v[150:153], v[180:183], v[118:121]
	v_mfma_f32_16x16x32_bf16 v[114:117], v[170:173], v[180:183], v[114:117]
	v_mfma_f32_16x16x32_bf16 v[98:101], v[170:173], v[190:193], v[98:101]
	v_mfma_f32_16x16x32_bf16 v[102:105], v[150:153], v[190:193], v[102:105]
	v_mfma_f32_16x16x32_bf16 v[84:87], v[150:153], v[198:201], v[84:87]
	v_mfma_f32_16x16x32_bf16 v[80:83], v[170:173], v[198:201], v[80:83]
	v_mfma_f32_16x16x32_bf16 v[64:67], v[170:173], v[206:209], v[64:67]
	v_mfma_f32_16x16x32_bf16 v[68:71], v[150:153], v[206:209], v[68:71]
	s_barrier
	s_add_i32 s18, s18, s96
	v_lshl_add_u64 v[178:179], s[2:3], 0, v[162:163]
	s_mov_b32 m0, s18
	ds_read_b128 v[174:177], v188 offset:16384
	ds_read_b128 v[180:183], v188 offset:17408
	ds_read_b128 v[184:187], v188 offset:18432
	ds_read_b128 v[190:193], v188 offset:19456
	ds_read_b128 v[194:197], v188 offset:20480
	ds_read_b128 v[198:201], v188 offset:21504
	ds_read_b128 v[202:205], v188 offset:22528
	ds_read_b128 v[206:209], v188 offset:23552
	global_load_lds_dwordx4 v162, s[2:3]
	s_add_i32 m0, s18, 0x2000
	v_lshl_add_u64 v[210:211], s[2:3], 0, v[158:159]
	s_add_u32 s2, s2, s48
	s_addc_u32 s3, s3, 0
	s_add_i32 s18, s38, s96
	global_load_lds_dwordx4 v[210:211], off
	v_lshl_add_u64 v[212:213], s[2:3], 0, v[162:163]
	s_mov_b32 m0, s18
	v_lshl_add_u64 v[214:215], s[2:3], 0, v[158:159]
	global_load_lds_dwordx4 v162, s[2:3]
	s_add_i32 m0, s18, 0x2000
	s_nop 0
	global_load_lds_dwordx4 v158, s[2:3]
	s_mov_b32 m0, s97
	s_nop 0
	global_load_lds_dwordx4 v164, s[42:43]
	s_mov_b32 m0, s22
	s_nop 0
	global_load_lds_dwordx4 v160, s[42:43]
	s_waitcnt vmcnt(8)
	s_waitcnt lgkmcnt(0)
	s_barrier
	v_mfma_f32_16x16x32_bf16 v[60:63], v[122:125], v[174:177], v[60:63]
	v_mfma_f32_16x16x32_bf16 v[56:59], v[138:141], v[174:177], v[56:59]
	v_mfma_f32_16x16x32_bf16 v[40:43], v[138:141], v[184:187], v[40:43]
	v_mfma_f32_16x16x32_bf16 v[44:47], v[122:125], v[184:187], v[44:47]
	v_mfma_f32_16x16x32_bf16 v[28:31], v[122:125], v[194:197], v[28:31]
	v_mfma_f32_16x16x32_bf16 v[24:27], v[138:141], v[194:197], v[24:27]
	v_mfma_f32_16x16x32_bf16 v[8:11], v[138:141], v[202:205], v[8:11]
	v_mfma_f32_16x16x32_bf16 v[12:15], v[122:125], v[202:205], v[12:15]
	v_mfma_f32_16x16x32_bf16 v[60:63], v[126:129], v[180:183], v[60:63]
	v_mfma_f32_16x16x32_bf16 v[56:59], v[142:145], v[180:183], v[56:59]
	v_mfma_f32_16x16x32_bf16 v[40:43], v[142:145], v[190:193], v[40:43]
	v_mfma_f32_16x16x32_bf16 v[44:47], v[126:129], v[190:193], v[44:47]
	v_mfma_f32_16x16x32_bf16 v[28:31], v[126:129], v[198:201], v[28:31]
	v_mfma_f32_16x16x32_bf16 v[24:27], v[142:145], v[198:201], v[24:27]
	v_mfma_f32_16x16x32_bf16 v[8:11], v[142:145], v[206:209], v[8:11]
	v_mfma_f32_16x16x32_bf16 v[12:15], v[126:129], v[206:209], v[12:15]
	v_mfma_f32_16x16x32_bf16 v[52:55], v[146:149], v[174:177], v[52:55]
	v_mfma_f32_16x16x32_bf16 v[48:51], v[154:157], v[174:177], v[48:51]
	v_mfma_f32_16x16x32_bf16 v[32:35], v[154:157], v[184:187], v[32:35]
	v_mfma_f32_16x16x32_bf16 v[36:39], v[146:149], v[184:187], v[36:39]
	v_mfma_f32_16x16x32_bf16 v[20:23], v[146:149], v[194:197], v[20:23]
	v_mfma_f32_16x16x32_bf16 v[16:19], v[154:157], v[194:197], v[16:19]
	v_mfma_f32_16x16x32_bf16 v[0:3], v[154:157], v[202:205], v[0:3]
	v_mfma_f32_16x16x32_bf16 v[4:7], v[146:149], v[202:205], v[4:7]
	v_mfma_f32_16x16x32_bf16 v[52:55], v[150:153], v[180:183], v[52:55]
	v_mfma_f32_16x16x32_bf16 v[48:51], v[170:173], v[180:183], v[48:51]
	v_mfma_f32_16x16x32_bf16 v[32:35], v[170:173], v[190:193], v[32:35]
	v_mfma_f32_16x16x32_bf16 v[36:39], v[150:153], v[190:193], v[36:39]
	v_mfma_f32_16x16x32_bf16 v[20:23], v[150:153], v[198:201], v[20:23]
	v_mfma_f32_16x16x32_bf16 v[16:19], v[170:173], v[198:201], v[16:19]
	v_mfma_f32_16x16x32_bf16 v[0:3], v[170:173], v[206:209], v[0:3]
	v_mfma_f32_16x16x32_bf16 v[4:7], v[150:153], v[206:209], v[4:7]
	s_barrier
; template <class Epi, class Sched, bool ALIGN_EPI = false, bool SP2 = false>
; __device__ __forceinline__ void gemm_phase(PG8_LAS unsigned char* lds, const Gemm g, const Sched& S, const Epi& E) {
;     ...
;         for (int t = (Epi::PEEL ? 2 : 0); t < nt; t += 2) {
;             const bool last = (t == nt - 2);
;             const char* a1 = cA + (size_t)(t + 1) * kstepA;
;             const char* a2 = last ? nA : cA + (size_t)(t + 2) * kstepA; const char* b2 = last ? nB : cB + (size_t)(t + 2) * kstepB;
;             const char* a3 = a2 + kstepA; const char* b3 = b2 + kstepB;
;             PG8_ITER(8);
;         }
	s_add_i32 s18, 0, 0x18000
	s_add_i32 s38, 0, 0x1c000
	v_add_u32_e32 v142, s18, v97
	v_add_u32_e32 v170, s38, v97
	ds_read_b128 v[122:125], v142
	ds_read_b128 v[126:129], v142 offset:1024
	ds_read_b128 v[138:141], v142 offset:2048
	ds_read_b128 v[142:145], v142 offset:3072
	ds_read_b128 v[146:149], v170
	ds_read_b128 v[150:153], v170 offset:1024
	ds_read_b128 v[154:157], v170 offset:2048
	ds_read_b128 v[170:173], v170 offset:3072
	s_add_u32 s2, s42, s98
	s_addc_u32 s3, s43, 0
	s_mov_b32 m0, s23
	ds_read_b128 v[174:177], v188 offset:32768
	ds_read_b128 v[180:183], v188 offset:33792
	ds_read_b128 v[184:187], v188 offset:34816
	ds_read_b128 v[190:193], v188 offset:35840
	ds_read_b128 v[194:197], v188 offset:36864
	ds_read_b128 v[198:201], v188 offset:37888
	ds_read_b128 v[202:205], v188 offset:38912
	ds_read_b128 v[206:209], v188 offset:39936
	global_load_lds_dwordx4 v164, s[2:3]
	s_mov_b32 m0, s19
	s_nop 0
	global_load_lds_dwordx4 v160, s[2:3]
	s_waitcnt vmcnt(8)
	s_waitcnt lgkmcnt(0)
	s_barrier
	v_mfma_f32_16x16x32_bf16 v[134:137], v[122:125], v[174:177], v[134:137]
	v_mfma_f32_16x16x32_bf16 v[130:133], v[138:141], v[174:177], v[130:133]
	v_mfma_f32_16x16x32_bf16 v[106:109], v[138:141], v[184:187], v[106:109]
	v_mfma_f32_16x16x32_bf16 v[110:113], v[122:125], v[184:187], v[110:113]
	v_mfma_f32_16x16x32_bf16 v[92:95], v[122:125], v[194:197], v[92:95]
	v_mfma_f32_16x16x32_bf16 v[88:91], v[138:141], v[194:197], v[88:91]
	v_mfma_f32_16x16x32_bf16 v[72:75], v[138:141], v[202:205], v[72:75]
	v_mfma_f32_16x16x32_bf16 v[76:79], v[122:125], v[202:205], v[76:79]
	v_mfma_f32_16x16x32_bf16 v[134:137], v[126:129], v[180:183], v[134:137]
	v_mfma_f32_16x16x32_bf16 v[130:133], v[142:145], v[180:183], v[130:133]
	v_mfma_f32_16x16x32_bf16 v[106:109], v[142:145], v[190:193], v[106:109]
	v_mfma_f32_16x16x32_bf16 v[110:113], v[126:129], v[190:193], v[110:113]
	v_mfma_f32_16x16x32_bf16 v[92:95], v[126:129], v[198:201], v[92:95]
	v_mfma_f32_16x16x32_bf16 v[88:91], v[142:145], v[198:201], v[88:91]
	v_mfma_f32_16x16x32_bf16 v[72:75], v[142:145], v[206:209], v[72:75]
	v_mfma_f32_16x16x32_bf16 v[76:79], v[126:129], v[206:209], v[76:79]
	v_mfma_f32_16x16x32_bf16 v[118:121], v[146:149], v[174:177], v[118:121]
	v_mfma_f32_16x16x32_bf16 v[114:117], v[154:157], v[174:177], v[114:117]
	v_mfma_f32_16x16x32_bf16 v[98:101], v[154:157], v[184:187], v[98:101]
	v_mfma_f32_16x16x32_bf16 v[102:105], v[146:149], v[184:187], v[102:105]
	v_mfma_f32_16x16x32_bf16 v[84:87], v[146:149], v[194:197], v[84:87]
	v_mfma_f32_16x16x32_bf16 v[80:83], v[154:157], v[194:197], v[80:83]
	v_mfma_f32_16x16x32_bf16 v[64:67], v[154:157], v[202:205], v[64:67]
	v_mfma_f32_16x16x32_bf16 v[68:71], v[146:149], v[202:205], v[68:71]
	v_mfma_f32_16x16x32_bf16 v[118:121], v[150:153], v[180:183], v[118:121]
	v_mfma_f32_16x16x32_bf16 v[114:117], v[170:173], v[180:183], v[114:117]
	v_mfma_f32_16x16x32_bf16 v[98:101], v[170:173], v[190:193], v[98:101]
	v_mfma_f32_16x16x32_bf16 v[102:105], v[150:153], v[190:193], v[102:105]
	v_mfma_f32_16x16x32_bf16 v[84:87], v[150:153], v[198:201], v[84:87]
	v_mfma_f32_16x16x32_bf16 v[80:83], v[170:173], v[198:201], v[80:83]
	v_mfma_f32_16x16x32_bf16 v[64:67], v[170:173], v[206:209], v[64:67]
	v_mfma_f32_16x16x32_bf16 v[68:71], v[150:153], v[206:209], v[68:71]
	s_barrier
	s_add_i32 s2, s18, s96
	v_lshl_add_u64 v[178:179], v[178:179], 0, s[36:37]
	s_mov_b32 m0, s2
	ds_read_b128 v[174:177], v188 offset:49152
	ds_read_b128 v[180:183], v188 offset:50176
	ds_read_b128 v[184:187], v188 offset:51200
	ds_read_b128 v[190:193], v188 offset:52224
	ds_read_b128 v[194:197], v188 offset:53248
	ds_read_b128 v[198:201], v188 offset:54272
	ds_read_b128 v[202:205], v188 offset:55296
	ds_read_b128 v[206:209], v188 offset:56320
	global_load_lds_dwordx4 v[178:179], off
	v_lshl_add_u64 v[178:179], v[210:211], 0, s[36:37]
	s_add_i32 m0, s2, 0x2000
	s_add_i32 s2, s38, s96
	global_load_lds_dwordx4 v[178:179], off
	v_lshl_add_u64 v[178:179], v[212:213], 0, s[36:37]
	s_mov_b32 m0, s2
	s_nop 0
	global_load_lds_dwordx4 v[178:179], off
	v_lshl_add_u64 v[178:179], v[214:215], 0, s[36:37]
	s_add_i32 m0, s2, 0x2000
	s_nop 0
	global_load_lds_dwordx4 v[178:179], off
	s_mov_b32 m0, s6
	s_nop 0
	global_load_lds_dwordx4 v164, s[44:45]
	s_mov_b32 m0, s56
	s_nop 0
	global_load_lds_dwordx4 v160, s[44:45]
	s_waitcnt vmcnt(8)
	s_waitcnt lgkmcnt(0)
	s_barrier
	v_mfma_f32_16x16x32_bf16 v[60:63], v[122:125], v[174:177], v[60:63]
	v_mfma_f32_16x16x32_bf16 v[56:59], v[138:141], v[174:177], v[56:59]
	v_mfma_f32_16x16x32_bf16 v[40:43], v[138:141], v[184:187], v[40:43]
	v_mfma_f32_16x16x32_bf16 v[44:47], v[122:125], v[184:187], v[44:47]
	v_mfma_f32_16x16x32_bf16 v[28:31], v[122:125], v[194:197], v[28:31]
	v_mfma_f32_16x16x32_bf16 v[24:27], v[138:141], v[194:197], v[24:27]
	v_mfma_f32_16x16x32_bf16 v[8:11], v[138:141], v[202:205], v[8:11]
	v_mfma_f32_16x16x32_bf16 v[12:15], v[122:125], v[202:205], v[12:15]
	v_mfma_f32_16x16x32_bf16 v[60:63], v[126:129], v[180:183], v[60:63]
	v_mfma_f32_16x16x32_bf16 v[56:59], v[142:145], v[180:183], v[56:59]
	v_mfma_f32_16x16x32_bf16 v[40:43], v[142:145], v[190:193], v[40:43]
	v_mfma_f32_16x16x32_bf16 v[44:47], v[126:129], v[190:193], v[44:47]
	v_mfma_f32_16x16x32_bf16 v[28:31], v[126:129], v[198:201], v[28:31]
	v_mfma_f32_16x16x32_bf16 v[24:27], v[142:145], v[198:201], v[24:27]
	v_mfma_f32_16x16x32_bf16 v[8:11], v[142:145], v[206:209], v[8:11]
	v_mfma_f32_16x16x32_bf16 v[12:15], v[126:129], v[206:209], v[12:15]
	v_mfma_f32_16x16x32_bf16 v[52:55], v[146:149], v[174:177], v[52:55]
	v_mfma_f32_16x16x32_bf16 v[48:51], v[154:157], v[174:177], v[48:51]
	v_mfma_f32_16x16x32_bf16 v[32:35], v[154:157], v[184:187], v[32:35]
	v_mfma_f32_16x16x32_bf16 v[36:39], v[146:149], v[184:187], v[36:39]
	v_mfma_f32_16x16x32_bf16 v[20:23], v[146:149], v[194:197], v[20:23]
	v_mfma_f32_16x16x32_bf16 v[16:19], v[154:157], v[194:197], v[16:19]
	v_mfma_f32_16x16x32_bf16 v[0:3], v[154:157], v[202:205], v[0:3]
	v_mfma_f32_16x16x32_bf16 v[4:7], v[146:149], v[202:205], v[4:7]
	v_mfma_f32_16x16x32_bf16 v[52:55], v[150:153], v[180:183], v[52:55]
	v_mfma_f32_16x16x32_bf16 v[48:51], v[170:173], v[180:183], v[48:51]
	v_mfma_f32_16x16x32_bf16 v[32:35], v[170:173], v[190:193], v[32:35]
	v_mfma_f32_16x16x32_bf16 v[36:39], v[150:153], v[190:193], v[36:39]
	v_mfma_f32_16x16x32_bf16 v[20:23], v[150:153], v[198:201], v[20:23]
	v_mfma_f32_16x16x32_bf16 v[16:19], v[170:173], v[198:201], v[16:19]
	v_mfma_f32_16x16x32_bf16 v[0:3], v[170:173], v[206:209], v[0:3]
	v_mfma_f32_16x16x32_bf16 v[4:7], v[150:153], v[206:209], v[4:7]
	s_barrier
	s_add_u32 s58, s58, 0x100
	s_addc_u32 s59, s59, 0
	s_add_u32 s24, s24, s49
	s_addc_u32 s25, s25, 0
	s_cmp_ge_u32 s10, s8
	s_cbranch_scc1 .LBB0_348

; template <class Epi, class Sched, bool ALIGN_EPI = false, bool SP2 = false>
; __device__ __forceinline__ void gemm_phase(PG8_LAS unsigned char* lds, const Gemm g, const Sched& S, const Epi& E) {
;     ...
;         const bool has_next = S.next(ui + 1, nxt);
;         const char* nA = has_next ? (const char*)g.A + (size_t)nxt.pm * tstepA : cA; const char* nB = has_next ? (const char*)g.Bt + (size_t)nxt.pn * tstepB : cB;
;     ...
;         if constexpr (Epi::PEEL) {
;             const char* a1 = cA + kstepA; const char* a2 = cA + 2 * kstepA; const char* b2 = cB + 2 * kstepB; const char* a3 = a2 + kstepA; const char* b3 = b2 + kstepB;
;             PG8_ITER(8);
.LBB0_477:
	s_ashr_i32 s27, s26, 31
	s_lshl_b64 s[2:3], s[26:27], 15
	v_readlane_b32 s10, v255, 15
	s_add_u32 s28, s10, s2
	v_readlane_b32 s2, v255, 16
	s_addc_u32 s29, s2, s3
	s_ashr_i32 s25, s24, 31
	s_lshl_b64 s[2:3], s[24:25], 19
	s_add_u32 s30, s19, s2
	s_addc_u32 s31, s22, s3
	s_add_u32 s44, s34, 0x800000
	s_addc_u32 s45, s35, 0
	s_add_u32 s42, s34, 0xc00000
	s_addc_u32 s43, s35, 0
	s_add_i32 s61, 0, 0x10000
	s_and_b64 s[2:3], s[40:41], exec
	s_cselect_b32 s25, s29, s35
	s_cselect_b32 s27, s28, s34
	s_add_i32 s97, 0, 0x14000
	v_add_u32_e32 v142, s61, v97
	v_add_u32_e32 v143, s97, v97
	ds_read_b128 v[0:3], v142
	ds_read_b128 v[4:7], v142 offset:1024
	ds_read_b128 v[8:11], v142 offset:2048
	ds_read_b128 v[12:15], v142 offset:3072
	ds_read_b128 v[16:19], v143
	s_waitcnt lgkmcnt(0)
	ds_read_b128 v[20:23], v143 offset:1024
	ds_read_b128 v[24:27], v143 offset:2048
	ds_read_b128 v[28:31], v143 offset:3072
	s_and_b64 s[2:3], s[40:41], exec
	s_cselect_b32 s57, s31, s1
	s_cselect_b32 s58, s30, s0
	s_add_u32 s2, s34, 0x404000
	s_addc_u32 s3, s35, 0
	s_add_i32 s59, s23, 0xc000
	s_mov_b32 m0, s59
	s_add_i32 s60, s23, 0xe000
	ds_read_b128 v[32:35], v156
	ds_read_b128 v[36:39], v156 offset:1024
	ds_read_b128 v[40:43], v156 offset:2048
	ds_read_b128 v[44:47], v156 offset:3072
	ds_read_b128 v[48:51], v156 offset:4096
	ds_read_b128 v[52:55], v156 offset:5120
	ds_read_b128 v[56:59], v156 offset:6144
	ds_read_b128 v[60:63], v156 offset:7168
	global_load_lds_dwordx4 v130, s[2:3]
	s_mov_b32 m0, s60
	s_nop 0
	global_load_lds_dwordx4 v134, s[2:3]
	s_waitcnt vmcnt(8)
	s_waitcnt lgkmcnt(0)
	s_barrier
	v_mfma_f32_16x16x32_bf16 v[88:91], v[0:3], v[56:59], 0
	v_mfma_f32_16x16x32_bf16 v[64:67], v[0:3], v[32:35], 0
	v_mfma_f32_16x16x32_bf16 v[68:71], v[8:11], v[32:35], 0
	v_mfma_f32_16x16x32_bf16 v[72:75], v[0:3], v[40:43], 0
	v_mfma_f32_16x16x32_bf16 v[76:79], v[8:11], v[40:43], 0
	v_mfma_f32_16x16x32_bf16 v[80:83], v[0:3], v[48:51], 0
	v_mfma_f32_16x16x32_bf16 v[84:87], v[8:11], v[48:51], 0
	v_mfma_f32_16x16x32_bf16 v[92:95], v[4:7], v[60:63], v[88:91]
	v_mfma_f32_16x16x32_bf16 v[88:91], v[8:11], v[56:59], 0
	v_mfma_f32_16x16x32_bf16 v[64:67], v[4:7], v[36:39], v[64:67]
	v_mfma_f32_16x16x32_bf16 v[68:71], v[12:15], v[36:39], v[68:71]
	v_mfma_f32_16x16x32_bf16 v[72:75], v[4:7], v[44:47], v[72:75]
	v_mfma_f32_16x16x32_bf16 v[76:79], v[12:15], v[44:47], v[76:79]
	v_mfma_f32_16x16x32_bf16 v[80:83], v[4:7], v[52:55], v[80:83]
	v_mfma_f32_16x16x32_bf16 v[84:87], v[12:15], v[52:55], v[84:87]
	v_mfma_f32_16x16x32_bf16 v[102:105], v[12:15], v[60:63], v[88:91]
	v_mfma_f32_16x16x32_bf16 v[88:91], v[16:19], v[32:35], 0
	v_mfma_f32_16x16x32_bf16 v[32:35], v[24:27], v[32:35], 0
	v_mfma_f32_16x16x32_bf16 v[110:113], v[20:23], v[36:39], v[88:91]
	v_mfma_f32_16x16x32_bf16 v[32:35], v[28:31], v[36:39], v[32:35]
	v_mfma_f32_16x16x32_bf16 v[36:39], v[16:19], v[40:43], 0
	v_mfma_f32_16x16x32_bf16 v[40:43], v[24:27], v[40:43], 0
	v_mfma_f32_16x16x32_bf16 v[36:39], v[20:23], v[44:47], v[36:39]
	v_mfma_f32_16x16x32_bf16 v[40:43], v[28:31], v[44:47], v[40:43]
	v_mfma_f32_16x16x32_bf16 v[44:47], v[16:19], v[48:51], 0
	v_mfma_f32_16x16x32_bf16 v[48:51], v[24:27], v[48:51], 0
	v_mfma_f32_16x16x32_bf16 v[44:47], v[20:23], v[52:55], v[44:47]
	v_mfma_f32_16x16x32_bf16 v[48:51], v[28:31], v[52:55], v[48:51]
	v_mfma_f32_16x16x32_bf16 v[52:55], v[16:19], v[56:59], 0
	v_mfma_f32_16x16x32_bf16 v[56:59], v[24:27], v[56:59], 0
	v_mfma_f32_16x16x32_bf16 v[52:55], v[20:23], v[60:63], v[52:55]
	v_mfma_f32_16x16x32_bf16 v[56:59], v[28:31], v[60:63], v[56:59]
	s_barrier
	v_lshl_add_u64 v[154:155], s[0:1], 0, v[132:133]
	s_mov_b64 s[2:3], 0x100
	s_add_i32 s61, s61, s9
	v_lshl_add_u64 v[144:145], v[154:155], 0, s[2:3]
	s_mov_b32 m0, s61
	v_lshl_add_u64 v[178:179], s[0:1], 0, v[136:137]
	s_add_i32 s96, s61, 0x2000
	ds_read_b128 v[60:63], v156 offset:16384
	ds_read_b128 v[88:91], v156 offset:17408
	ds_read_b128 v[98:101], v156 offset:18432
	ds_read_b128 v[106:109], v156 offset:19456
	ds_read_b128 v[114:117], v156 offset:20480
	ds_read_b128 v[118:121], v156 offset:21504
	ds_read_b128 v[122:125], v156 offset:22528
	ds_read_b128 v[126:129], v156 offset:23552
	global_load_lds_dwordx4 v[144:145], off
	v_lshl_add_u64 v[144:145], v[178:179], 0, s[2:3]
	s_add_u32 s2, s0, 0x40100
	s_mov_b32 m0, s96
	s_addc_u32 s3, s1, 0
	s_add_i32 s97, s97, s9
	global_load_lds_dwordx4 v[144:145], off
	s_mov_b32 m0, s97
	s_add_i32 s98, s97, 0x2000
	global_load_lds_dwordx4 v132, s[2:3]
	s_mov_b32 m0, s98
	s_nop 0
	global_load_lds_dwordx4 v136, s[2:3]
	s_mov_b32 m0, s23
	s_nop 0
	global_load_lds_dwordx4 v130, s[44:45]
	s_mov_b32 m0, s39
	s_nop 0
	global_load_lds_dwordx4 v134, s[44:45]
	s_waitcnt vmcnt(8)
	s_waitcnt lgkmcnt(0)
	s_barrier
	v_mfma_f32_16x16x32_bf16 v[144:147], v[0:3], v[60:63], 0
	v_mfma_f32_16x16x32_bf16 v[158:161], v[0:3], v[98:101], 0
	v_mfma_f32_16x16x32_bf16 v[166:169], v[0:3], v[114:117], 0
	v_mfma_f32_16x16x32_bf16 v[0:3], v[0:3], v[122:125], 0
	v_mfma_f32_16x16x32_bf16 v[146:149], v[4:7], v[88:91], v[144:147]
	v_mfma_f32_16x16x32_bf16 v[158:161], v[4:7], v[106:109], v[158:161]
	v_mfma_f32_16x16x32_bf16 v[166:169], v[4:7], v[118:121], v[166:169]
	v_mfma_f32_16x16x32_bf16 v[0:3], v[4:7], v[126:129], v[0:3]
	v_mfma_f32_16x16x32_bf16 v[4:7], v[8:11], v[122:125], 0
	v_mfma_f32_16x16x32_bf16 v[150:153], v[8:11], v[60:63], 0
	v_mfma_f32_16x16x32_bf16 v[162:165], v[8:11], v[98:101], 0
	v_mfma_f32_16x16x32_bf16 v[170:173], v[8:11], v[114:117], 0
	v_mfma_f32_16x16x32_bf16 v[4:7], v[12:15], v[126:129], v[4:7]
	v_mfma_f32_16x16x32_bf16 v[150:153], v[12:15], v[88:91], v[150:153]
	v_mfma_f32_16x16x32_bf16 v[162:165], v[12:15], v[106:109], v[162:165]
	v_mfma_f32_16x16x32_bf16 v[170:173], v[12:15], v[118:121], v[170:173]
	v_mfma_f32_16x16x32_bf16 v[8:11], v[16:19], v[60:63], 0
	v_mfma_f32_16x16x32_bf16 v[12:15], v[20:23], v[88:91], v[8:11]
	v_mfma_f32_16x16x32_bf16 v[8:11], v[24:27], v[60:63], 0
	v_mfma_f32_16x16x32_bf16 v[174:177], v[28:31], v[88:91], v[8:11]
	v_mfma_f32_16x16x32_bf16 v[8:11], v[16:19], v[98:101], 0
	v_mfma_f32_16x16x32_bf16 v[188:191], v[20:23], v[106:109], v[8:11]
	v_mfma_f32_16x16x32_bf16 v[8:11], v[24:27], v[98:101], 0
	v_mfma_f32_16x16x32_bf16 v[192:195], v[28:31], v[106:109], v[8:11]
	v_mfma_f32_16x16x32_bf16 v[8:11], v[16:19], v[114:117], 0
	v_mfma_f32_16x16x32_bf16 v[196:199], v[20:23], v[118:121], v[8:11]
	v_mfma_f32_16x16x32_bf16 v[8:11], v[24:27], v[114:117], 0
	v_mfma_f32_16x16x32_bf16 v[200:203], v[28:31], v[118:121], v[8:11]
	v_mfma_f32_16x16x32_bf16 v[8:11], v[16:19], v[122:125], 0
	v_mfma_f32_16x16x32_bf16 v[204:207], v[20:23], v[126:129], v[8:11]
	v_mfma_f32_16x16x32_bf16 v[8:11], v[24:27], v[122:125], 0
	v_mfma_f32_16x16x32_bf16 v[208:211], v[28:31], v[126:129], v[8:11]
	s_barrier
	s_add_i32 s99, 0, 0x18000
	s_add_i32 vcc_hi, 0, 0x1c000
	v_add_u32_e32 v144, s99, v97
	v_add_u32_e32 v145, vcc_hi, v97
	s_nop 0
	ds_read_b128 v[8:11], v144
	ds_read_b128 v[20:23], v144 offset:1024
	ds_read_b128 v[28:31], v144 offset:2048
	ds_read_b128 v[212:215], v144 offset:3072
	ds_read_b128 v[216:219], v145
	ds_read_b128 v[220:223], v145 offset:1024
	ds_read_b128 v[234:237], v145 offset:2048
	ds_read_b128 v[238:241], v145 offset:3072
	s_add_u32 s2, s34, 0x804000
	s_addc_u32 s3, s35, 0
	s_mov_b32 m0, s46
	ds_read_b128 v[16:19], v156 offset:32768
	ds_read_b128 v[24:27], v156 offset:33792
	ds_read_b128 v[242:245], v156 offset:34816
	ds_read_b128 v[246:249], v156 offset:35840
	ds_read_b128 v[228:231], v156 offset:36864
	ds_read_b128 v[180:183], v156 offset:37888
	ds_read_b128 v[184:187], v156 offset:38912
	ds_read_b128 v[224:227], v156 offset:39936
	global_load_lds_dwordx4 v130, s[2:3]
	s_mov_b32 m0, s47
	s_nop 0
	global_load_lds_dwordx4 v134, s[2:3]
	s_waitcnt vmcnt(8)
	s_waitcnt lgkmcnt(0)
	s_barrier
	v_mfma_f32_16x16x32_bf16 v[60:63], v[8:11], v[16:19], v[64:67]
	v_mfma_f32_16x16x32_bf16 v[122:125], v[20:23], v[24:27], v[60:63]
	v_mfma_f32_16x16x32_bf16 v[60:63], v[28:31], v[16:19], v[68:71]
	v_mfma_f32_16x16x32_bf16 v[114:117], v[212:215], v[24:27], v[60:63]
	v_mfma_f32_16x16x32_bf16 v[60:63], v[8:11], v[242:245], v[72:75]
	v_mfma_f32_16x16x32_bf16 v[106:109], v[20:23], v[246:249], v[60:63]
	v_mfma_f32_16x16x32_bf16 v[60:63], v[28:31], v[242:245], v[76:79]
	v_mfma_f32_16x16x32_bf16 v[98:101], v[212:215], v[246:249], v[60:63]
	v_mfma_f32_16x16x32_bf16 v[60:63], v[8:11], v[228:231], v[80:83]
	v_mfma_f32_16x16x32_bf16 v[88:91], v[20:23], v[180:183], v[60:63]
	v_mfma_f32_16x16x32_bf16 v[60:63], v[28:31], v[228:231], v[84:87]
	v_mfma_f32_16x16x32_bf16 v[80:83], v[212:215], v[180:183], v[60:63]
	v_mfma_f32_16x16x32_bf16 v[60:63], v[8:11], v[184:187], v[92:95]
	v_mfma_f32_16x16x32_bf16 v[72:75], v[20:23], v[224:227], v[60:63]
	v_mfma_f32_16x16x32_bf16 v[60:63], v[28:31], v[184:187], v[102:105]
	v_mfma_f32_16x16x32_bf16 v[60:63], v[212:215], v[224:227], v[60:63]
	v_mfma_f32_16x16x32_bf16 v[64:67], v[216:219], v[16:19], v[110:113]
	v_mfma_f32_16x16x32_bf16 v[16:19], v[234:237], v[16:19], v[32:35]
	v_mfma_f32_16x16x32_bf16 v[118:121], v[238:241], v[24:27], v[16:19]
	v_mfma_f32_16x16x32_bf16 v[16:19], v[216:219], v[242:245], v[36:39]
	v_mfma_f32_16x16x32_bf16 v[110:113], v[220:223], v[246:249], v[16:19]
	v_mfma_f32_16x16x32_bf16 v[16:19], v[234:237], v[242:245], v[40:43]
	v_mfma_f32_16x16x32_bf16 v[102:105], v[238:241], v[246:249], v[16:19]
	v_mfma_f32_16x16x32_bf16 v[16:19], v[216:219], v[228:231], v[44:47]
	v_mfma_f32_16x16x32_bf16 v[92:95], v[220:223], v[180:183], v[16:19]
	v_mfma_f32_16x16x32_bf16 v[16:19], v[234:237], v[228:231], v[48:51]
	v_mfma_f32_16x16x32_bf16 v[84:87], v[238:241], v[180:183], v[16:19]
	v_mfma_f32_16x16x32_bf16 v[16:19], v[216:219], v[184:187], v[52:55]
	v_mfma_f32_16x16x32_bf16 v[76:79], v[220:223], v[224:227], v[16:19]
	v_mfma_f32_16x16x32_bf16 v[16:19], v[234:237], v[184:187], v[56:59]
	v_mfma_f32_16x16x32_bf16 v[126:129], v[220:223], v[24:27], v[64:67]
	v_mfma_f32_16x16x32_bf16 v[68:71], v[238:241], v[224:227], v[16:19]
	s_barrier
; template <class Epi, class Sched, bool ALIGN_EPI = false, bool SP2 = false>
; __device__ __forceinline__ void gemm_phase(PG8_LAS unsigned char* lds, const Gemm g, const Sched& S, const Epi& E) {
;     ...
;         if constexpr (Epi::PEEL) {
;             const char* a1 = cA + kstepA; const char* a2 = cA + 2 * kstepA; const char* b2 = cB + 2 * kstepB; const char* a3 = a2 + kstepA; const char* b3 = b2 + kstepB;
;             PG8_ITER(8);
;         }
;         for (int t = (Epi::PEEL ? 2 : 0); t < nt; t += 2) {
;             const bool last = (t == nt - 2);
;             const char* a1 = cA + (size_t)(t + 1) * kstepA;
;             const char* a2 = last ? nA : cA + (size_t)(t + 2) * kstepA; const char* b2 = last ? nB : cB + (size_t)(t + 2) * kstepB;
;             const char* a3 = a2 + kstepA; const char* b3 = b2 + kstepB;
;             PG8_ITER(8);
	s_mov_b64 s[2:3], 0x180
	s_add_i32 s99, s99, s9
	s_nop 1
	v_lshl_add_u64 v[16:17], v[154:155], 0, s[2:3]
	s_mov_b32 m0, s99
	s_add_i32 vcc_lo, s99, 0x2000
	ds_read_b128 v[36:39], v156 offset:49152
	ds_read_b128 v[44:47], v156 offset:50176
	ds_read_b128 v[180:183], v156 offset:51200
	ds_read_b128 v[184:187], v156 offset:52224
	ds_read_b128 v[224:227], v156 offset:53248
	ds_read_b128 v[228:231], v156 offset:54272
	ds_read_b128 v[242:245], v156 offset:55296
	ds_read_b128 v[246:249], v156 offset:56320
	global_load_lds_dwordx4 v[16:17], off
	v_lshl_add_u64 v[16:17], v[178:179], 0, s[2:3]
	s_add_u32 s2, s0, 0x40180
	s_mov_b32 m0, vcc_lo
	s_addc_u32 s3, s1, 0
	s_add_i32 vcc_hi, vcc_hi, s9
	global_load_lds_dwordx4 v[16:17], off
	s_mov_b32 m0, vcc_hi
	s_add_i32 s38, vcc_hi, 0x2000
	global_load_lds_dwordx4 v132, s[2:3]
	s_mov_b32 m0, s38
	s_nop 0
	global_load_lds_dwordx4 v136, s[2:3]
	s_mov_b32 m0, s49
	s_nop 0
	global_load_lds_dwordx4 v130, s[42:43]
	s_mov_b32 m0, s50
	s_nop 0
	global_load_lds_dwordx4 v134, s[42:43]
	s_waitcnt vmcnt(8)
	s_waitcnt lgkmcnt(0)
	s_barrier
	v_mfma_f32_16x16x32_bf16 v[16:19], v[8:11], v[36:39], v[146:149]
	v_mfma_f32_16x16x32_bf16 v[56:59], v[20:23], v[44:47], v[16:19]
	v_mfma_f32_16x16x32_bf16 v[16:19], v[28:31], v[36:39], v[150:153]
	v_mfma_f32_16x16x32_bf16 v[48:51], v[212:215], v[44:47], v[16:19]
	v_mfma_f32_16x16x32_bf16 v[16:19], v[8:11], v[180:183], v[158:161]
	v_mfma_f32_16x16x32_bf16 v[40:43], v[20:23], v[184:187], v[16:19]
	v_mfma_f32_16x16x32_bf16 v[16:19], v[28:31], v[180:183], v[162:165]
	v_mfma_f32_16x16x32_bf16 v[32:35], v[212:215], v[184:187], v[16:19]
	v_mfma_f32_16x16x32_bf16 v[16:19], v[8:11], v[224:227], v[166:169]
	v_mfma_f32_16x16x32_bf16 v[0:3], v[8:11], v[242:245], v[0:3]
	v_mfma_f32_16x16x32_bf16 v[24:27], v[20:23], v[228:231], v[16:19]
	v_mfma_f32_16x16x32_bf16 v[16:19], v[28:31], v[224:227], v[170:173]
	v_mfma_f32_16x16x32_bf16 v[8:11], v[20:23], v[246:249], v[0:3]
	v_mfma_f32_16x16x32_bf16 v[0:3], v[28:31], v[242:245], v[4:7]
	v_mfma_f32_16x16x32_bf16 v[16:19], v[212:215], v[228:231], v[16:19]
	v_mfma_f32_16x16x32_bf16 v[0:3], v[212:215], v[246:249], v[0:3]
	v_mfma_f32_16x16x32_bf16 v[4:7], v[216:219], v[36:39], v[12:15]
	v_mfma_f32_16x16x32_bf16 v[64:67], v[220:223], v[44:47], v[4:7]
	v_mfma_f32_16x16x32_bf16 v[4:7], v[234:237], v[36:39], v[174:177]
	v_mfma_f32_16x16x32_bf16 v[52:55], v[238:241], v[44:47], v[4:7]
	v_mfma_f32_16x16x32_bf16 v[4:7], v[216:219], v[180:183], v[188:191]
	v_mfma_f32_16x16x32_bf16 v[44:47], v[220:223], v[184:187], v[4:7]
	v_mfma_f32_16x16x32_bf16 v[4:7], v[234:237], v[180:183], v[192:195]
	v_mfma_f32_16x16x32_bf16 v[36:39], v[238:241], v[184:187], v[4:7]
	v_mfma_f32_16x16x32_bf16 v[4:7], v[216:219], v[224:227], v[196:199]
	v_mfma_f32_16x16x32_bf16 v[28:31], v[220:223], v[228:231], v[4:7]
	v_mfma_f32_16x16x32_bf16 v[4:7], v[234:237], v[224:227], v[200:203]
	v_mfma_f32_16x16x32_bf16 v[20:23], v[238:241], v[228:231], v[4:7]
	v_mfma_f32_16x16x32_bf16 v[4:7], v[216:219], v[242:245], v[204:207]
	v_mfma_f32_16x16x32_bf16 v[12:15], v[220:223], v[246:249], v[4:7]
	v_mfma_f32_16x16x32_bf16 v[4:7], v[234:237], v[242:245], v[208:211]
	v_mfma_f32_16x16x32_bf16 v[4:7], v[238:241], v[246:249], v[4:7]
	s_barrier
	s_add_u32 s3, s0, 0x200
	s_addc_u32 s2, s1, 0
	s_add_u32 s0, s34, 0xc04000
	s_addc_u32 s1, s35, 0
	s_mov_b32 s18, 0
.LBB0_478:
	ds_read_b128 v[146:149], v142
	ds_read_b128 v[150:153], v142 offset:1024
	ds_read_b128 v[158:161], v142 offset:2048
	ds_read_b128 v[162:165], v142 offset:3072
	ds_read_b128 v[166:169], v143
	ds_read_b128 v[170:173], v143 offset:1024
	ds_read_b128 v[174:177], v143 offset:2048
	ds_read_b128 v[180:183], v143 offset:3072
	s_add_u32 s10, s0, 0x3fc000
	s_addc_u32 s11, s1, 0
	s_cmp_eq_u32 s18, 12
	s_cselect_b32 s44, s27, s10
	s_cselect_b32 s45, s25, s11
	s_cselect_b32 s42, s58, s3
	s_cselect_b32 s43, s57, s2
	s_add_u32 s34, s44, 0x400000
	s_addc_u32 s35, s45, 0
	s_mov_b32 m0, s59
	ds_read_b128 v[184:187], v156
	ds_read_b128 v[188:191], v156 offset:1024
	ds_read_b128 v[192:195], v156 offset:2048
	ds_read_b128 v[196:199], v156 offset:3072
	ds_read_b128 v[200:203], v156 offset:4096
	ds_read_b128 v[204:207], v156 offset:5120
	ds_read_b128 v[208:211], v156 offset:6144
	ds_read_b128 v[212:215], v156 offset:7168
	global_load_lds_dwordx4 v140, s[0:1]
	s_mov_b32 m0, s60
	s_nop 0
	global_load_lds_dwordx4 v138, s[0:1]
	s_waitcnt vmcnt(8)
	s_waitcnt lgkmcnt(0)
	s_barrier
	v_mfma_f32_16x16x32_bf16 v[122:125], v[146:149], v[184:187], v[122:125]
	v_mfma_f32_16x16x32_bf16 v[114:117], v[158:161], v[184:187], v[114:117]
	v_mfma_f32_16x16x32_bf16 v[98:101], v[158:161], v[192:195], v[98:101]
	v_mfma_f32_16x16x32_bf16 v[106:109], v[146:149], v[192:195], v[106:109]
	v_mfma_f32_16x16x32_bf16 v[88:91], v[146:149], v[200:203], v[88:91]
	v_mfma_f32_16x16x32_bf16 v[80:83], v[158:161], v[200:203], v[80:83]
	v_mfma_f32_16x16x32_bf16 v[60:63], v[158:161], v[208:211], v[60:63]
	v_mfma_f32_16x16x32_bf16 v[72:75], v[146:149], v[208:211], v[72:75]
	v_mfma_f32_16x16x32_bf16 v[122:125], v[150:153], v[188:191], v[122:125]
	v_mfma_f32_16x16x32_bf16 v[114:117], v[162:165], v[188:191], v[114:117]
	v_mfma_f32_16x16x32_bf16 v[98:101], v[162:165], v[196:199], v[98:101]
	v_mfma_f32_16x16x32_bf16 v[106:109], v[150:153], v[196:199], v[106:109]
	v_mfma_f32_16x16x32_bf16 v[88:91], v[150:153], v[204:207], v[88:91]
	v_mfma_f32_16x16x32_bf16 v[80:83], v[162:165], v[204:207], v[80:83]
	v_mfma_f32_16x16x32_bf16 v[60:63], v[162:165], v[212:215], v[60:63]
	v_mfma_f32_16x16x32_bf16 v[72:75], v[150:153], v[212:215], v[72:75]
	v_mfma_f32_16x16x32_bf16 v[126:129], v[166:169], v[184:187], v[126:129]
	v_mfma_f32_16x16x32_bf16 v[118:121], v[174:177], v[184:187], v[118:121]
	v_mfma_f32_16x16x32_bf16 v[102:105], v[174:177], v[192:195], v[102:105]
	v_mfma_f32_16x16x32_bf16 v[110:113], v[166:169], v[192:195], v[110:113]
	v_mfma_f32_16x16x32_bf16 v[92:95], v[166:169], v[200:203], v[92:95]
	v_mfma_f32_16x16x32_bf16 v[84:87], v[174:177], v[200:203], v[84:87]
	v_mfma_f32_16x16x32_bf16 v[68:71], v[174:177], v[208:211], v[68:71]
	v_mfma_f32_16x16x32_bf16 v[76:79], v[166:169], v[208:211], v[76:79]
	v_mfma_f32_16x16x32_bf16 v[126:129], v[170:173], v[188:191], v[126:129]
	v_mfma_f32_16x16x32_bf16 v[118:121], v[180:183], v[188:191], v[118:121]
	v_mfma_f32_16x16x32_bf16 v[102:105], v[180:183], v[196:199], v[102:105]
	v_mfma_f32_16x16x32_bf16 v[110:113], v[170:173], v[196:199], v[110:113]
	v_mfma_f32_16x16x32_bf16 v[92:95], v[170:173], v[204:207], v[92:95]
	v_mfma_f32_16x16x32_bf16 v[84:87], v[180:183], v[204:207], v[84:87]
	v_mfma_f32_16x16x32_bf16 v[68:71], v[180:183], v[212:215], v[68:71]
	v_mfma_f32_16x16x32_bf16 v[76:79], v[170:173], v[212:215], v[76:79]
	s_barrier
	s_mov_b32 m0, s61
	s_add_u32 s10, s42, 0x40000
	ds_read_b128 v[184:187], v156 offset:16384
	ds_read_b128 v[188:191], v156 offset:17408
	ds_read_b128 v[192:195], v156 offset:18432
	ds_read_b128 v[196:199], v156 offset:19456
	ds_read_b128 v[200:203], v156 offset:20480
	ds_read_b128 v[204:207], v156 offset:21504
	ds_read_b128 v[208:211], v156 offset:22528
	ds_read_b128 v[212:215], v156 offset:23552
	global_load_lds_dwordx4 v132, s[42:43]
	s_mov_b32 m0, s96
	s_addc_u32 s11, s43, 0
	global_load_lds_dwordx4 v136, s[42:43]
	s_mov_b32 m0, s97
	s_nop 0
	global_load_lds_dwordx4 v132, s[10:11]
	s_mov_b32 m0, s98
	s_nop 0
	global_load_lds_dwordx4 v136, s[10:11]
	s_mov_b32 m0, s23
	s_nop 0
	global_load_lds_dwordx4 v130, s[44:45]
	s_mov_b32 m0, s39
	s_nop 0
	global_load_lds_dwordx4 v134, s[44:45]
	s_waitcnt vmcnt(8)
	s_waitcnt lgkmcnt(0)
	s_barrier
	v_mfma_f32_16x16x32_bf16 v[56:59], v[146:149], v[184:187], v[56:59]
	v_mfma_f32_16x16x32_bf16 v[48:51], v[158:161], v[184:187], v[48:51]
	v_mfma_f32_16x16x32_bf16 v[32:35], v[158:161], v[192:195], v[32:35]
	v_mfma_f32_16x16x32_bf16 v[40:43], v[146:149], v[192:195], v[40:43]
	v_mfma_f32_16x16x32_bf16 v[24:27], v[146:149], v[200:203], v[24:27]
	v_mfma_f32_16x16x32_bf16 v[16:19], v[158:161], v[200:203], v[16:19]
	v_mfma_f32_16x16x32_bf16 v[0:3], v[158:161], v[208:211], v[0:3]
	v_mfma_f32_16x16x32_bf16 v[8:11], v[146:149], v[208:211], v[8:11]
	v_mfma_f32_16x16x32_bf16 v[56:59], v[150:153], v[188:191], v[56:59]
	v_mfma_f32_16x16x32_bf16 v[48:51], v[162:165], v[188:191], v[48:51]
	v_mfma_f32_16x16x32_bf16 v[32:35], v[162:165], v[196:199], v[32:35]
	v_mfma_f32_16x16x32_bf16 v[40:43], v[150:153], v[196:199], v[40:43]
	v_mfma_f32_16x16x32_bf16 v[24:27], v[150:153], v[204:207], v[24:27]
	v_mfma_f32_16x16x32_bf16 v[16:19], v[162:165], v[204:207], v[16:19]
	v_mfma_f32_16x16x32_bf16 v[0:3], v[162:165], v[212:215], v[0:3]
	v_mfma_f32_16x16x32_bf16 v[8:11], v[150:153], v[212:215], v[8:11]
	v_mfma_f32_16x16x32_bf16 v[64:67], v[166:169], v[184:187], v[64:67]
	v_mfma_f32_16x16x32_bf16 v[52:55], v[174:177], v[184:187], v[52:55]
	v_mfma_f32_16x16x32_bf16 v[36:39], v[174:177], v[192:195], v[36:39]
	v_mfma_f32_16x16x32_bf16 v[44:47], v[166:169], v[192:195], v[44:47]
	v_mfma_f32_16x16x32_bf16 v[28:31], v[166:169], v[200:203], v[28:31]
	v_mfma_f32_16x16x32_bf16 v[20:23], v[174:177], v[200:203], v[20:23]
	v_mfma_f32_16x16x32_bf16 v[4:7], v[174:177], v[208:211], v[4:7]
	v_mfma_f32_16x16x32_bf16 v[12:15], v[166:169], v[208:211], v[12:15]
	v_mfma_f32_16x16x32_bf16 v[64:67], v[170:173], v[188:191], v[64:67]
	v_mfma_f32_16x16x32_bf16 v[52:55], v[180:183], v[188:191], v[52:55]
	v_mfma_f32_16x16x32_bf16 v[36:39], v[180:183], v[196:199], v[36:39]
	v_mfma_f32_16x16x32_bf16 v[44:47], v[170:173], v[196:199], v[44:47]
	v_mfma_f32_16x16x32_bf16 v[28:31], v[170:173], v[204:207], v[28:31]
	v_mfma_f32_16x16x32_bf16 v[20:23], v[180:183], v[204:207], v[20:23]
	v_mfma_f32_16x16x32_bf16 v[4:7], v[180:183], v[212:215], v[4:7]
	v_mfma_f32_16x16x32_bf16 v[12:15], v[170:173], v[212:215], v[12:15]
	s_barrier
	ds_read_b128 v[146:149], v144
	ds_read_b128 v[150:153], v144 offset:1024
	ds_read_b128 v[158:161], v144 offset:2048
	ds_read_b128 v[162:165], v144 offset:3072
	ds_read_b128 v[166:169], v145
	ds_read_b128 v[170:173], v145 offset:1024
	ds_read_b128 v[174:177], v145 offset:2048
	ds_read_b128 v[180:183], v145 offset:3072
	s_add_u32 s10, s44, 0x4000
	s_addc_u32 s11, s45, 0
	s_mov_b32 m0, s46
	ds_read_b128 v[184:187], v156 offset:32768
	ds_read_b128 v[188:191], v156 offset:33792
	ds_read_b128 v[192:195], v156 offset:34816
	ds_read_b128 v[196:199], v156 offset:35840
	ds_read_b128 v[200:203], v156 offset:36864
	ds_read_b128 v[204:207], v156 offset:37888
	ds_read_b128 v[208:211], v156 offset:38912
	ds_read_b128 v[212:215], v156 offset:39936
	global_load_lds_dwordx4 v130, s[10:11]
	s_mov_b32 m0, s47
	s_nop 0
	global_load_lds_dwordx4 v134, s[10:11]
	s_waitcnt vmcnt(8)
	s_waitcnt lgkmcnt(0)
	s_barrier
; #define PG8_BAR __builtin_amdgcn_s_barrier()
; template <class Epi, class Sched, bool ALIGN_EPI = false, bool SP2 = false>
; __device__ __forceinline__ void gemm_phase(PG8_LAS unsigned char* lds, const Gemm g, const Sched& S, const Epi& E) {
;     ...
;         if constexpr (Epi::PEEL) {
;             const char* a1 = cA + kstepA; const char* a2 = cA + 2 * kstepA; const char* b2 = cB + 2 * kstepB; const char* a3 = a2 + kstepA; const char* b3 = b2 + kstepB;
;             PG8_ITER(8);
;         }
;         for (int t = (Epi::PEEL ? 2 : 0); t < nt; t += 2) {
;             const bool last = (t == nt - 2);
;             const char* a1 = cA + (size_t)(t + 1) * kstepA;
;             const char* a2 = last ? nA : cA + (size_t)(t + 2) * kstepA; const char* b2 = last ? nB : cB + (size_t)(t + 2) * kstepB;
;             const char* a3 = a2 + kstepA; const char* b3 = b2 + kstepB;
;             PG8_ITER(8);
;         }
;     ...
;         if constexpr (ALIGN_EPI) { if (wr == 0) PG8_BAR; }
	v_mfma_f32_16x16x32_bf16 v[122:125], v[146:149], v[184:187], v[122:125]
	v_mfma_f32_16x16x32_bf16 v[114:117], v[158:161], v[184:187], v[114:117]
	v_mfma_f32_16x16x32_bf16 v[98:101], v[158:161], v[192:195], v[98:101]
	v_mfma_f32_16x16x32_bf16 v[106:109], v[146:149], v[192:195], v[106:109]
	v_mfma_f32_16x16x32_bf16 v[88:91], v[146:149], v[200:203], v[88:91]
	v_mfma_f32_16x16x32_bf16 v[80:83], v[158:161], v[200:203], v[80:83]
	v_mfma_f32_16x16x32_bf16 v[60:63], v[158:161], v[208:211], v[60:63]
	v_mfma_f32_16x16x32_bf16 v[72:75], v[146:149], v[208:211], v[72:75]
	v_mfma_f32_16x16x32_bf16 v[122:125], v[150:153], v[188:191], v[122:125]
	v_mfma_f32_16x16x32_bf16 v[114:117], v[162:165], v[188:191], v[114:117]
	v_mfma_f32_16x16x32_bf16 v[98:101], v[162:165], v[196:199], v[98:101]
	v_mfma_f32_16x16x32_bf16 v[106:109], v[150:153], v[196:199], v[106:109]
	v_mfma_f32_16x16x32_bf16 v[88:91], v[150:153], v[204:207], v[88:91]
	v_mfma_f32_16x16x32_bf16 v[80:83], v[162:165], v[204:207], v[80:83]
	v_mfma_f32_16x16x32_bf16 v[60:63], v[162:165], v[212:215], v[60:63]
	v_mfma_f32_16x16x32_bf16 v[72:75], v[150:153], v[212:215], v[72:75]
	v_mfma_f32_16x16x32_bf16 v[126:129], v[166:169], v[184:187], v[126:129]
	v_mfma_f32_16x16x32_bf16 v[118:121], v[174:177], v[184:187], v[118:121]
	v_mfma_f32_16x16x32_bf16 v[102:105], v[174:177], v[192:195], v[102:105]
	v_mfma_f32_16x16x32_bf16 v[110:113], v[166:169], v[192:195], v[110:113]
	v_mfma_f32_16x16x32_bf16 v[92:95], v[166:169], v[200:203], v[92:95]
	v_mfma_f32_16x16x32_bf16 v[84:87], v[174:177], v[200:203], v[84:87]
	v_mfma_f32_16x16x32_bf16 v[68:71], v[174:177], v[208:211], v[68:71]
	v_mfma_f32_16x16x32_bf16 v[76:79], v[166:169], v[208:211], v[76:79]
	v_mfma_f32_16x16x32_bf16 v[126:129], v[170:173], v[188:191], v[126:129]
	v_mfma_f32_16x16x32_bf16 v[118:121], v[180:183], v[188:191], v[118:121]
	v_mfma_f32_16x16x32_bf16 v[102:105], v[180:183], v[196:199], v[102:105]
	v_mfma_f32_16x16x32_bf16 v[110:113], v[170:173], v[196:199], v[110:113]
	v_mfma_f32_16x16x32_bf16 v[92:95], v[170:173], v[204:207], v[92:95]
	v_mfma_f32_16x16x32_bf16 v[84:87], v[180:183], v[204:207], v[84:87]
	v_mfma_f32_16x16x32_bf16 v[68:71], v[180:183], v[212:215], v[68:71]
	v_mfma_f32_16x16x32_bf16 v[76:79], v[170:173], v[212:215], v[76:79]
	s_barrier
	s_mov_b32 m0, s99
	s_add_u32 s100, s42, 0x80
	s_addc_u32 s101, s43, 0
	s_add_u32 s10, s42, 0x40080
	ds_read_b128 v[184:187], v156 offset:49152
	ds_read_b128 v[188:191], v156 offset:50176
	ds_read_b128 v[192:195], v156 offset:51200
	ds_read_b128 v[196:199], v156 offset:52224
	ds_read_b128 v[200:203], v156 offset:53248
	ds_read_b128 v[204:207], v156 offset:54272
	ds_read_b128 v[208:211], v156 offset:55296
	ds_read_b128 v[212:215], v156 offset:56320
	global_load_lds_dwordx4 v132, s[100:101]
	s_mov_b32 m0, vcc_lo
	s_addc_u32 s11, s43, 0
	global_load_lds_dwordx4 v136, s[100:101]
	s_mov_b32 m0, vcc_hi
	s_nop 0
	global_load_lds_dwordx4 v132, s[10:11]
	s_mov_b32 m0, s38
	s_nop 0
	global_load_lds_dwordx4 v136, s[10:11]
	s_mov_b32 m0, s49
	s_nop 0
	global_load_lds_dwordx4 v130, s[34:35]
	s_mov_b32 m0, s50
	s_nop 0
	global_load_lds_dwordx4 v134, s[34:35]
	s_waitcnt vmcnt(8)
	s_waitcnt lgkmcnt(0)
	s_barrier
	v_mfma_f32_16x16x32_bf16 v[56:59], v[146:149], v[184:187], v[56:59]
	v_mfma_f32_16x16x32_bf16 v[48:51], v[158:161], v[184:187], v[48:51]
	v_mfma_f32_16x16x32_bf16 v[32:35], v[158:161], v[192:195], v[32:35]
	v_mfma_f32_16x16x32_bf16 v[40:43], v[146:149], v[192:195], v[40:43]
	v_mfma_f32_16x16x32_bf16 v[24:27], v[146:149], v[200:203], v[24:27]
	v_mfma_f32_16x16x32_bf16 v[16:19], v[158:161], v[200:203], v[16:19]
	v_mfma_f32_16x16x32_bf16 v[0:3], v[158:161], v[208:211], v[0:3]
	v_mfma_f32_16x16x32_bf16 v[8:11], v[146:149], v[208:211], v[8:11]
	v_mfma_f32_16x16x32_bf16 v[56:59], v[150:153], v[188:191], v[56:59]
	v_mfma_f32_16x16x32_bf16 v[48:51], v[162:165], v[188:191], v[48:51]
	v_mfma_f32_16x16x32_bf16 v[32:35], v[162:165], v[196:199], v[32:35]
	v_mfma_f32_16x16x32_bf16 v[40:43], v[150:153], v[196:199], v[40:43]
	v_mfma_f32_16x16x32_bf16 v[24:27], v[150:153], v[204:207], v[24:27]
	v_mfma_f32_16x16x32_bf16 v[16:19], v[162:165], v[204:207], v[16:19]
	v_mfma_f32_16x16x32_bf16 v[0:3], v[162:165], v[212:215], v[0:3]
	v_mfma_f32_16x16x32_bf16 v[8:11], v[150:153], v[212:215], v[8:11]
	v_mfma_f32_16x16x32_bf16 v[64:67], v[166:169], v[184:187], v[64:67]
	v_mfma_f32_16x16x32_bf16 v[52:55], v[174:177], v[184:187], v[52:55]
	v_mfma_f32_16x16x32_bf16 v[36:39], v[174:177], v[192:195], v[36:39]
	v_mfma_f32_16x16x32_bf16 v[44:47], v[166:169], v[192:195], v[44:47]
	v_mfma_f32_16x16x32_bf16 v[28:31], v[166:169], v[200:203], v[28:31]
	v_mfma_f32_16x16x32_bf16 v[20:23], v[174:177], v[200:203], v[20:23]
	v_mfma_f32_16x16x32_bf16 v[4:7], v[174:177], v[208:211], v[4:7]
	v_mfma_f32_16x16x32_bf16 v[12:15], v[166:169], v[208:211], v[12:15]
	v_mfma_f32_16x16x32_bf16 v[64:67], v[170:173], v[188:191], v[64:67]
	v_mfma_f32_16x16x32_bf16 v[52:55], v[180:183], v[188:191], v[52:55]
	v_mfma_f32_16x16x32_bf16 v[36:39], v[180:183], v[196:199], v[36:39]
	v_mfma_f32_16x16x32_bf16 v[44:47], v[170:173], v[196:199], v[44:47]
	v_mfma_f32_16x16x32_bf16 v[28:31], v[170:173], v[204:207], v[28:31]
	v_mfma_f32_16x16x32_bf16 v[20:23], v[180:183], v[204:207], v[20:23]
	v_mfma_f32_16x16x32_bf16 v[4:7], v[180:183], v[212:215], v[4:7]
	v_mfma_f32_16x16x32_bf16 v[12:15], v[170:173], v[212:215], v[12:15]
	s_barrier
	s_add_i32 s18, s18, 2
	s_add_u32 s3, s3, 0x100
	s_addc_u32 s2, s2, 0
	s_add_u32 s0, s0, 0x800000
	s_addc_u32 s1, s1, 0
	s_cmp_gt_u32 s18, 13
	s_cbranch_scc0 .LBB0_478
	s_and_b64 vcc, exec, s[16:17]
	s_cbranch_vccz .LBB0_481
	s_barrier
